# scan pipelined across chunks (two light barriers per chunk, y-chain of last step carried into next chunk, cross-chunk LDS prefetch) + NSA sel hoist + top-k scalar compare
# baseline (speedup 1.0000x reference)
; #define LAS __attribute__((address_space(3)))
; __device__ __forceinline__ void scan_phase(const Args& a, LAS unsigned char* lds, int tid, int lane, int wave, int G, int bid) {
;     ...
;         for (int ch = 0; ch < SEQ / SC_CH; ++ch) {
;             LAS float* buf = OP + (ch & 1) * SC_CH * SC_STEP;
;             if (stager) { SCAN_PUT8(buf + ldP, rKK); SCAN_PUT8(buf + ldP + 64, rAK); SCAN_PUT8(buf + ldP + 192, rK); SCAN_PUT8(buf + ldP + 256, rR);
;                 *(LAS f32x4*)(buf + ldD) = rD0; *(LAS f32x4*)(buf + ldD + 16 * SC_STEP) = rD1;
;                 if (sid < 64) { LAS float* vd = VV + (ch & 1) * 512 + (vst >> 2) * 64 + (vhalf * 8) * 4 + (vst & 3); vd[0] = bf_lo(rV.x); vd[4] = bf_hi(rV.x); vd[8] = bf_lo(rV.y); vd[12] = bf_hi(rV.y); vd[16] = bf_lo(rV.z); vd[20] = bf_hi(rV.z); vd[24] = bf_lo(rV.w); vd[28] = bf_hi(rV.w); } }
;             __syncthreads();
;             if (ch + 1 < SEQ / SC_CH) SCAN_ISSUE(ch + 1);
;             if (wave < 4) {
;                 const LAS float* op0 = buf + 4 * c; const LAS float* vv0 = VV + (ch & 1) * 512 + row * 4;
;                 f32x4 nkk = *(const LAS f32x4*)(op0), nak = *(const LAS f32x4*)(op0 + 64), nw = *(const LAS f32x4*)(op0 + 128), nk = *(const LAS f32x4*)(op0 + 192), nr = *(const LAS f32x4*)(op0 + 256);
;                 f32x4 nv[4] = {*(const LAS f32x4*)(vv0), *(const LAS f32x4*)(vv0 + 64), *(const LAS f32x4*)(vv0 + 128), *(const LAS f32x4*)(vv0 + 192)};
; #pragma unroll 1
;                 for (int oh = 0; oh < 2; ++oh) {
;                     const LAS float* opb = op0 + oh * 16 * SC_STEP;
;                     const f32x4 vq[4] = {nv[0], nv[1], nv[2], nv[3]};
;                     { const int ohn = oh < 1 ? 1 : 1;
; #pragma unroll
;                       for (int q = 0; q < 4; ++q) nv[q] = *(const LAS f32x4*)(vv0 + (ohn * 4 + q) * 64); }
;                     float yk = 0.f;
; #pragma unroll
;                     for (int i = 0; i < 16; ++i) {
;                         const f32x4 kk4 = nkk, ak4 = nak, w4 = nw, k4 = nk, r4 = nr; const float vv = vq[i >> 2][i & 3];
;                         { const int nx = (i < 15) ? (i + 1) : (oh < 1 ? 16 : 15); const LAS float* on = opb + nx * SC_STEP;
;                           nkk = *(const LAS f32x4*)(on); nak = *(const LAS f32x4*)(on + 64); nw = *(const LAS f32x4*)(on + 128); nk = *(const LAS f32x4*)(on + 192); nr = *(const LAS f32x4*)(on + 256); }
.Lsp_pro_c:
	s_waitcnt lgkmcnt(0)
	s_barrier
	s_and_b64 vcc, exec, s[38:39]
	s_cbranch_vccz .Lsp_loop
	v_mov_b32_e32 v101, v99
	v_mov_b32_e32 v103, v119
	v_mov_b32_e32 v146, v123
	v_add_u32_e32 v126, 2048, v123
	ds_read_b128 v[76:79], v103
	ds_read_b128 v[36:39], v101
	ds_read_b128 v[40:43], v101 offset:256
	ds_read_b128 v[44:47], v101 offset:512
	ds_read_b128 v[48:51], v101 offset:768
	ds_read_b128 v[52:55], v101 offset:1024
	ds_read_b128 v[56:59], v101 offset:1344
	ds_read_b128 v[60:63], v101 offset:1600
	ds_read_b128 v[64:67], v101 offset:1856
	ds_read_b128 v[68:71], v101 offset:2112
	ds_read_b128 v[72:75], v101 offset:2368
.Lsp_loop:
	s_and_b64 vcc, exec, s[38:39]
	s_cbranch_vccz .Lsp_stage
	s_add_i32 s15, s54, 1
	s_and_b32 s15, s15, 1
	s_mul_i32 s23, s15, 0xa800
	v_add_u32_e32 v122, s23, v99
	v_lshl_add_u32 v124, s15, 11, v119
	s_waitcnt lgkmcnt(5)
	v_pk_mul_f32 v[88:89], v[84:85], v[36:37]
	v_pk_mul_f32 v[90:91], v[84:85], v[184:185]
	v_pk_fma_f32 v[88:89], v[86:87], v[38:39], v[88:89]
	v_pk_fma_f32 v[90:91], v[86:87], v[186:187], v[90:91]
	v_add_f32_e32 v92, v88, v89
	v_add_f32_e32 v118, v90, v91
	v_pk_mul_f32 v[120:121], v[48:49], v[76:77] op_sel:[0,0] op_sel_hi:[1,0]
	v_add_f32_dpp v92, v92, v92 row_ror:8 row_mask:0xf bank_mask:0xf bound_ctrl:1
	v_add_f32_dpp v118, v118, v118 row_ror:8 row_mask:0xf bank_mask:0xf bound_ctrl:1
	v_pk_mul_f32 v[238:239], v[50:51], v[76:77] op_sel:[0,0] op_sel_hi:[1,0]
	v_add_f32_dpp v92, v92, v92 row_ror:4 row_mask:0xf bank_mask:0xf bound_ctrl:1
	v_add_f32_dpp v118, v118, v118 row_ror:4 row_mask:0xf bank_mask:0xf bound_ctrl:1
	v_pk_fma_f32 v[240:241], v[84:85], v[44:45], v[120:121]
	v_add_f32_dpp v92, v92, v92 row_ror:2 row_mask:0xf bank_mask:0xf bound_ctrl:1
	v_add_f32_dpp v118, v118, v118 row_ror:2 row_mask:0xf bank_mask:0xf bound_ctrl:1
	v_pk_fma_f32 v[242:243], v[86:87], v[46:47], v[238:239]
	v_add_f32_dpp v92, v92, v92 row_ror:1 row_mask:0xf bank_mask:0xf bound_ctrl:1
	v_add_f32_dpp v118, v118, v118 row_ror:1 row_mask:0xf bank_mask:0xf bound_ctrl:1
	v_pk_fma_f32 v[84:85], v[92:93], v[40:41], v[240:241] op_sel_hi:[0,1,1] neg_lo:[1,0,0] neg_hi:[1,0,0]
	v_pk_fma_f32 v[86:87], v[92:93], v[42:43], v[242:243] op_sel_hi:[0,1,1] neg_lo:[1,0,0] neg_hi:[1,0,0]
	v_fmac_f32_e32 v244, v144, v118
	ds_write_b32 v126, v244 offset:1024
	ds_read_b128 v[148:151], v101 offset:2688
	ds_read_b128 v[152:155], v101 offset:2944
	ds_read_b128 v[156:159], v101 offset:3200
	ds_read_b128 v[160:163], v101 offset:3456
	ds_read_b128 v[164:167], v101 offset:3712
	s_waitcnt lgkmcnt(6)
	v_pk_mul_f32 v[88:89], v[84:85], v[56:57]
	v_pk_mul_f32 v[90:91], v[84:85], v[52:53]
	v_pk_fma_f32 v[88:89], v[86:87], v[58:59], v[88:89]
	v_pk_fma_f32 v[90:91], v[86:87], v[54:55], v[90:91]
	v_add_f32_e32 v92, v88, v89
	v_add_f32_e32 v118, v90, v91
	v_pk_mul_f32 v[120:121], v[68:69], v[76:77] op_sel:[0,1] op_sel_hi:[1,1]
	v_add_f32_dpp v92, v92, v92 row_ror:8 row_mask:0xf bank_mask:0xf bound_ctrl:1
	v_add_f32_dpp v118, v118, v118 row_ror:8 row_mask:0xf bank_mask:0xf bound_ctrl:1
	v_pk_mul_f32 v[238:239], v[70:71], v[76:77] op_sel:[0,1] op_sel_hi:[1,1]
	v_add_f32_dpp v92, v92, v92 row_ror:4 row_mask:0xf bank_mask:0xf bound_ctrl:1
	v_add_f32_dpp v118, v118, v118 row_ror:4 row_mask:0xf bank_mask:0xf bound_ctrl:1
	v_pk_fma_f32 v[240:241], v[84:85], v[64:65], v[120:121]
	v_add_f32_dpp v92, v92, v92 row_ror:2 row_mask:0xf bank_mask:0xf bound_ctrl:1
	v_add_f32_dpp v118, v118, v118 row_ror:2 row_mask:0xf bank_mask:0xf bound_ctrl:1
	v_pk_fma_f32 v[242:243], v[86:87], v[66:67], v[238:239]
	v_add_f32_dpp v92, v92, v92 row_ror:1 row_mask:0xf bank_mask:0xf bound_ctrl:1
	v_add_f32_dpp v118, v118, v118 row_ror:1 row_mask:0xf bank_mask:0xf bound_ctrl:1
	v_pk_fma_f32 v[84:85], v[92:93], v[60:61], v[240:241] op_sel_hi:[0,1,1] neg_lo:[1,0,0] neg_hi:[1,0,0]
	v_pk_fma_f32 v[86:87], v[92:93], v[62:63], v[242:243] op_sel_hi:[0,1,1] neg_lo:[1,0,0] neg_hi:[1,0,0]
	v_mul_f32_e32 v145, v127, v118
	ds_read_b128 v[168:171], v101 offset:4032
	ds_read_b128 v[172:175], v101 offset:4288
	ds_read_b128 v[176:179], v101 offset:4544
	ds_read_b128 v[180:183], v101 offset:4800
	ds_read_b128 v[184:187], v101 offset:5056
	ds_read_b128 v[80:83], v103 offset:256
	s_waitcnt lgkmcnt(6)
	v_pk_mul_f32 v[88:89], v[84:85], v[148:149]
	v_pk_mul_f32 v[90:91], v[84:85], v[72:73]
	v_pk_fma_f32 v[88:89], v[86:87], v[150:151], v[88:89]
	v_pk_fma_f32 v[90:91], v[86:87], v[74:75], v[90:91]
	v_add_f32_e32 v92, v88, v89
	v_add_f32_e32 v118, v90, v91
	v_pk_mul_f32 v[120:121], v[160:161], v[78:79] op_sel:[0,0] op_sel_hi:[1,0]
	v_add_f32_dpp v92, v92, v92 row_ror:8 row_mask:0xf bank_mask:0xf bound_ctrl:1
	v_add_f32_dpp v118, v118, v118 row_ror:8 row_mask:0xf bank_mask:0xf bound_ctrl:1
	v_pk_mul_f32 v[238:239], v[162:163], v[78:79] op_sel:[0,0] op_sel_hi:[1,0]
	v_add_f32_dpp v92, v92, v92 row_ror:4 row_mask:0xf bank_mask:0xf bound_ctrl:1
	v_add_f32_dpp v118, v118, v118 row_ror:4 row_mask:0xf bank_mask:0xf bound_ctrl:1
	v_pk_fma_f32 v[240:241], v[84:85], v[156:157], v[120:121]
	v_add_f32_dpp v92, v92, v92 row_ror:2 row_mask:0xf bank_mask:0xf bound_ctrl:1
	v_add_f32_dpp v118, v118, v118 row_ror:2 row_mask:0xf bank_mask:0xf bound_ctrl:1
	v_pk_fma_f32 v[242:243], v[86:87], v[158:159], v[238:239]
	v_add_f32_dpp v92, v92, v92 row_ror:1 row_mask:0xf bank_mask:0xf bound_ctrl:1
	v_add_f32_dpp v118, v118, v118 row_ror:1 row_mask:0xf bank_mask:0xf bound_ctrl:1
	v_pk_fma_f32 v[84:85], v[92:93], v[152:153], v[240:241] op_sel_hi:[0,1,1] neg_lo:[1,0,0] neg_hi:[1,0,0]
	v_pk_fma_f32 v[86:87], v[92:93], v[154:155], v[242:243] op_sel_hi:[0,1,1] neg_lo:[1,0,0] neg_hi:[1,0,0]
	v_fmac_f32_e32 v145, v129, v118
	ds_read_b128 v[36:39], v101 offset:5376
	ds_read_b128 v[40:43], v101 offset:5632
	ds_read_b128 v[44:47], v101 offset:5888
	ds_read_b128 v[48:51], v101 offset:6144
	ds_read_b128 v[52:55], v101 offset:6400
	s_waitcnt lgkmcnt(6)
; #define LAS __attribute__((address_space(3)))
; __device__ __forceinline__ float allred16_dpp(float x) { x = dpp_add<0x128>(x); x = dpp_add<0x124>(x); x = dpp_add<0x122>(x); x = dpp_add<0x121>(x); return x; }
; __device__ __forceinline__ void scan_phase(const Args& a, LAS unsigned char* lds, int tid, int lane, int wave, int G, int bid) {
;     ...
;                     for (int i = 0; i < 16; ++i) {
;                         const f32x4 kk4 = nkk, ak4 = nak, w4 = nw, k4 = nk, r4 = nr; const float vv = vq[i >> 2][i & 3];
;                         { const int nx = (i < 15) ? (i + 1) : (oh < 1 ? 16 : 15); const LAS float* on = opb + nx * SC_STEP;
;                           nkk = *(const LAS f32x4*)(on); nak = *(const LAS f32x4*)(on + 64); nw = *(const LAS f32x4*)(on + 128); nk = *(const LAS f32x4*)(on + 192); nr = *(const LAS f32x4*)(on + 256); }
;                         f32x2 t = Sa * (f32x2){kk4[0], kk4[1]}; t = __builtin_elementwise_fma(Sb, (f32x2){kk4[2], kk4[3]}, t);
;                         float sa = t.x + t.y;
;                         sa = allred16_dpp(sa);
;                         const f32x2 nsa2 = (f32x2){-sa, -sa}, vv2 = (f32x2){vv, vv};
;                         f32x2 ua = vv2 * (f32x2){k4[0], k4[1]}, ub = vv2 * (f32x2){k4[2], k4[3]};
;                         ua = __builtin_elementwise_fma(nsa2, (f32x2){ak4[0], ak4[1]}, ua); ub = __builtin_elementwise_fma(nsa2, (f32x2){ak4[2], ak4[3]}, ub);
;                         Sa = __builtin_elementwise_fma(Sa, (f32x2){w4[0], w4[1]}, ua); Sb = __builtin_elementwise_fma(Sb, (f32x2){w4[2], w4[3]}, ub);
;                         f32x2 yy = Sa * (f32x2){r4[0], r4[1]}; yy = __builtin_elementwise_fma(Sb, (f32x2){r4[2], r4[3]}, yy);
;                         float y = yy.x + yy.y;
;                         y = allred16_dpp(y);
;                         yk = fmaf(wsel[i], y, yk);
	v_pk_mul_f32 v[88:89], v[84:85], v[168:169]
	v_pk_mul_f32 v[90:91], v[84:85], v[164:165]
	v_pk_fma_f32 v[88:89], v[86:87], v[170:171], v[88:89]
	v_pk_fma_f32 v[90:91], v[86:87], v[166:167], v[90:91]
	v_add_f32_e32 v92, v88, v89
	v_add_f32_e32 v118, v90, v91
	v_pk_mul_f32 v[120:121], v[180:181], v[78:79] op_sel:[0,1] op_sel_hi:[1,1]
	v_add_f32_dpp v92, v92, v92 row_ror:8 row_mask:0xf bank_mask:0xf bound_ctrl:1
	v_add_f32_dpp v118, v118, v118 row_ror:8 row_mask:0xf bank_mask:0xf bound_ctrl:1
	v_pk_mul_f32 v[238:239], v[182:183], v[78:79] op_sel:[0,1] op_sel_hi:[1,1]
	v_add_f32_dpp v92, v92, v92 row_ror:4 row_mask:0xf bank_mask:0xf bound_ctrl:1
	v_add_f32_dpp v118, v118, v118 row_ror:4 row_mask:0xf bank_mask:0xf bound_ctrl:1
	v_pk_fma_f32 v[240:241], v[84:85], v[176:177], v[120:121]
	v_add_f32_dpp v92, v92, v92 row_ror:2 row_mask:0xf bank_mask:0xf bound_ctrl:1
	v_add_f32_dpp v118, v118, v118 row_ror:2 row_mask:0xf bank_mask:0xf bound_ctrl:1
	v_pk_fma_f32 v[242:243], v[86:87], v[178:179], v[238:239]
	v_add_f32_dpp v92, v92, v92 row_ror:1 row_mask:0xf bank_mask:0xf bound_ctrl:1
	v_add_f32_dpp v118, v118, v118 row_ror:1 row_mask:0xf bank_mask:0xf bound_ctrl:1
	v_pk_fma_f32 v[84:85], v[92:93], v[172:173], v[240:241] op_sel_hi:[0,1,1] neg_lo:[1,0,0] neg_hi:[1,0,0]
	v_pk_fma_f32 v[86:87], v[92:93], v[174:175], v[242:243] op_sel_hi:[0,1,1] neg_lo:[1,0,0] neg_hi:[1,0,0]
	v_fmac_f32_e32 v145, v131, v118
	ds_read_b128 v[56:59], v101 offset:6720
	ds_read_b128 v[60:63], v101 offset:6976
	ds_read_b128 v[64:67], v101 offset:7232
	ds_read_b128 v[68:71], v101 offset:7488
	ds_read_b128 v[72:75], v101 offset:7744
	s_waitcnt lgkmcnt(5)
	s_barrier
	v_pk_mul_f32 v[88:89], v[84:85], v[36:37]
	v_pk_mul_f32 v[90:91], v[84:85], v[184:185]
	v_pk_fma_f32 v[88:89], v[86:87], v[38:39], v[88:89]
	v_pk_fma_f32 v[90:91], v[86:87], v[186:187], v[90:91]
	v_add_f32_e32 v92, v88, v89
	v_add_f32_e32 v118, v90, v91
	v_pk_mul_f32 v[120:121], v[48:49], v[80:81] op_sel:[0,0] op_sel_hi:[1,0]
	v_add_f32_dpp v92, v92, v92 row_ror:8 row_mask:0xf bank_mask:0xf bound_ctrl:1
	v_add_f32_dpp v118, v118, v118 row_ror:8 row_mask:0xf bank_mask:0xf bound_ctrl:1
	v_pk_mul_f32 v[238:239], v[50:51], v[80:81] op_sel:[0,0] op_sel_hi:[1,0]
	v_add_f32_dpp v92, v92, v92 row_ror:4 row_mask:0xf bank_mask:0xf bound_ctrl:1
	v_add_f32_dpp v118, v118, v118 row_ror:4 row_mask:0xf bank_mask:0xf bound_ctrl:1
	v_pk_fma_f32 v[240:241], v[84:85], v[44:45], v[120:121]
	v_add_f32_dpp v92, v92, v92 row_ror:2 row_mask:0xf bank_mask:0xf bound_ctrl:1
	v_add_f32_dpp v118, v118, v118 row_ror:2 row_mask:0xf bank_mask:0xf bound_ctrl:1
	v_pk_fma_f32 v[242:243], v[86:87], v[46:47], v[238:239]
	v_add_f32_dpp v92, v92, v92 row_ror:1 row_mask:0xf bank_mask:0xf bound_ctrl:1
	v_add_f32_dpp v118, v118, v118 row_ror:1 row_mask:0xf bank_mask:0xf bound_ctrl:1
	v_pk_fma_f32 v[84:85], v[92:93], v[40:41], v[240:241] op_sel_hi:[0,1,1] neg_lo:[1,0,0] neg_hi:[1,0,0]
	v_pk_fma_f32 v[86:87], v[92:93], v[42:43], v[242:243] op_sel_hi:[0,1,1] neg_lo:[1,0,0] neg_hi:[1,0,0]
	v_fmac_f32_e32 v145, v132, v118
	ds_read_b128 v[148:151], v101 offset:8064
	ds_read_b128 v[152:155], v101 offset:8320
	ds_read_b128 v[156:159], v101 offset:8576
	ds_read_b128 v[160:163], v101 offset:8832
	ds_read_b128 v[164:167], v101 offset:9088
	s_waitcnt lgkmcnt(5)
	v_pk_mul_f32 v[88:89], v[84:85], v[56:57]
	v_pk_mul_f32 v[90:91], v[84:85], v[52:53]
	v_pk_fma_f32 v[88:89], v[86:87], v[58:59], v[88:89]
	v_pk_fma_f32 v[90:91], v[86:87], v[54:55], v[90:91]
	v_add_f32_e32 v92, v88, v89
	v_add_f32_e32 v118, v90, v91
	v_pk_mul_f32 v[120:121], v[68:69], v[80:81] op_sel:[0,1] op_sel_hi:[1,1]
	v_add_f32_dpp v92, v92, v92 row_ror:8 row_mask:0xf bank_mask:0xf bound_ctrl:1
	v_add_f32_dpp v118, v118, v118 row_ror:8 row_mask:0xf bank_mask:0xf bound_ctrl:1
	v_pk_mul_f32 v[238:239], v[70:71], v[80:81] op_sel:[0,1] op_sel_hi:[1,1]
	v_add_f32_dpp v92, v92, v92 row_ror:4 row_mask:0xf bank_mask:0xf bound_ctrl:1
	v_add_f32_dpp v118, v118, v118 row_ror:4 row_mask:0xf bank_mask:0xf bound_ctrl:1
	v_pk_fma_f32 v[240:241], v[84:85], v[64:65], v[120:121]
	v_add_f32_dpp v92, v92, v92 row_ror:2 row_mask:0xf bank_mask:0xf bound_ctrl:1
	v_add_f32_dpp v118, v118, v118 row_ror:2 row_mask:0xf bank_mask:0xf bound_ctrl:1
	v_pk_fma_f32 v[242:243], v[86:87], v[66:67], v[238:239]
	v_add_f32_dpp v92, v92, v92 row_ror:1 row_mask:0xf bank_mask:0xf bound_ctrl:1
	v_add_f32_dpp v118, v118, v118 row_ror:1 row_mask:0xf bank_mask:0xf bound_ctrl:1
	v_pk_fma_f32 v[84:85], v[92:93], v[60:61], v[240:241] op_sel_hi:[0,1,1] neg_lo:[1,0,0] neg_hi:[1,0,0]
	v_pk_fma_f32 v[86:87], v[92:93], v[62:63], v[242:243] op_sel_hi:[0,1,1] neg_lo:[1,0,0] neg_hi:[1,0,0]
	v_fmac_f32_e32 v145, v133, v118
	ds_read_b128 v[168:171], v101 offset:9408
	ds_read_b128 v[172:175], v101 offset:9664
	ds_read_b128 v[176:179], v101 offset:9920
	ds_read_b128 v[180:183], v101 offset:10176
	ds_read_b128 v[184:187], v101 offset:10432
	ds_read_b128 v[76:79], v103 offset:512
	s_waitcnt lgkmcnt(6)
; #define LAS __attribute__((address_space(3)))
; __device__ __forceinline__ float allred16_dpp(float x) { x = dpp_add<0x128>(x); x = dpp_add<0x124>(x); x = dpp_add<0x122>(x); x = dpp_add<0x121>(x); return x; }
; __device__ __forceinline__ void scan_phase(const Args& a, LAS unsigned char* lds, int tid, int lane, int wave, int G, int bid) {
;     ...
;                     for (int i = 0; i < 16; ++i) {
;                         const f32x4 kk4 = nkk, ak4 = nak, w4 = nw, k4 = nk, r4 = nr; const float vv = vq[i >> 2][i & 3];
;                         { const int nx = (i < 15) ? (i + 1) : (oh < 1 ? 16 : 15); const LAS float* on = opb + nx * SC_STEP;
;                           nkk = *(const LAS f32x4*)(on); nak = *(const LAS f32x4*)(on + 64); nw = *(const LAS f32x4*)(on + 128); nk = *(const LAS f32x4*)(on + 192); nr = *(const LAS f32x4*)(on + 256); }
;                         f32x2 t = Sa * (f32x2){kk4[0], kk4[1]}; t = __builtin_elementwise_fma(Sb, (f32x2){kk4[2], kk4[3]}, t);
;                         float sa = t.x + t.y;
;                         sa = allred16_dpp(sa);
;                         const f32x2 nsa2 = (f32x2){-sa, -sa}, vv2 = (f32x2){vv, vv};
;                         f32x2 ua = vv2 * (f32x2){k4[0], k4[1]}, ub = vv2 * (f32x2){k4[2], k4[3]};
;                         ua = __builtin_elementwise_fma(nsa2, (f32x2){ak4[0], ak4[1]}, ua); ub = __builtin_elementwise_fma(nsa2, (f32x2){ak4[2], ak4[3]}, ub);
;                         Sa = __builtin_elementwise_fma(Sa, (f32x2){w4[0], w4[1]}, ua); Sb = __builtin_elementwise_fma(Sb, (f32x2){w4[2], w4[3]}, ub);
;                         f32x2 yy = Sa * (f32x2){r4[0], r4[1]}; yy = __builtin_elementwise_fma(Sb, (f32x2){r4[2], r4[3]}, yy);
;                         float y = yy.x + yy.y;
;                         y = allred16_dpp(y);
;                         yk = fmaf(wsel[i], y, yk);
	v_pk_mul_f32 v[88:89], v[84:85], v[148:149]
	v_pk_mul_f32 v[90:91], v[84:85], v[72:73]
	v_pk_fma_f32 v[88:89], v[86:87], v[150:151], v[88:89]
	v_pk_fma_f32 v[90:91], v[86:87], v[74:75], v[90:91]
	v_add_f32_e32 v92, v88, v89
	v_add_f32_e32 v118, v90, v91
	v_pk_mul_f32 v[120:121], v[160:161], v[82:83] op_sel:[0,0] op_sel_hi:[1,0]
	v_add_f32_dpp v92, v92, v92 row_ror:8 row_mask:0xf bank_mask:0xf bound_ctrl:1
	v_add_f32_dpp v118, v118, v118 row_ror:8 row_mask:0xf bank_mask:0xf bound_ctrl:1
	v_pk_mul_f32 v[238:239], v[162:163], v[82:83] op_sel:[0,0] op_sel_hi:[1,0]
	v_add_f32_dpp v92, v92, v92 row_ror:4 row_mask:0xf bank_mask:0xf bound_ctrl:1
	v_add_f32_dpp v118, v118, v118 row_ror:4 row_mask:0xf bank_mask:0xf bound_ctrl:1
	v_pk_fma_f32 v[240:241], v[84:85], v[156:157], v[120:121]
	v_add_f32_dpp v92, v92, v92 row_ror:2 row_mask:0xf bank_mask:0xf bound_ctrl:1
	v_add_f32_dpp v118, v118, v118 row_ror:2 row_mask:0xf bank_mask:0xf bound_ctrl:1
	v_pk_fma_f32 v[242:243], v[86:87], v[158:159], v[238:239]
	v_add_f32_dpp v92, v92, v92 row_ror:1 row_mask:0xf bank_mask:0xf bound_ctrl:1
	v_add_f32_dpp v118, v118, v118 row_ror:1 row_mask:0xf bank_mask:0xf bound_ctrl:1
	v_pk_fma_f32 v[84:85], v[92:93], v[152:153], v[240:241] op_sel_hi:[0,1,1] neg_lo:[1,0,0] neg_hi:[1,0,0]
	v_pk_fma_f32 v[86:87], v[92:93], v[154:155], v[242:243] op_sel_hi:[0,1,1] neg_lo:[1,0,0] neg_hi:[1,0,0]
	v_fmac_f32_e32 v145, v134, v118
	ds_read_b128 v[36:39], v101 offset:10752
	ds_read_b128 v[40:43], v101 offset:11008
	ds_read_b128 v[44:47], v101 offset:11264
	ds_read_b128 v[48:51], v101 offset:11520
	ds_read_b128 v[52:55], v101 offset:11776
	s_waitcnt lgkmcnt(6)
	v_pk_mul_f32 v[88:89], v[84:85], v[168:169]
	v_pk_mul_f32 v[90:91], v[84:85], v[164:165]
	v_pk_fma_f32 v[88:89], v[86:87], v[170:171], v[88:89]
	v_pk_fma_f32 v[90:91], v[86:87], v[166:167], v[90:91]
	v_add_f32_e32 v92, v88, v89
	v_add_f32_e32 v118, v90, v91
	v_pk_mul_f32 v[120:121], v[180:181], v[82:83] op_sel:[0,1] op_sel_hi:[1,1]
	v_add_f32_dpp v92, v92, v92 row_ror:8 row_mask:0xf bank_mask:0xf bound_ctrl:1
	v_add_f32_dpp v118, v118, v118 row_ror:8 row_mask:0xf bank_mask:0xf bound_ctrl:1
	v_pk_mul_f32 v[238:239], v[182:183], v[82:83] op_sel:[0,1] op_sel_hi:[1,1]
	v_add_f32_dpp v92, v92, v92 row_ror:4 row_mask:0xf bank_mask:0xf bound_ctrl:1
	v_add_f32_dpp v118, v118, v118 row_ror:4 row_mask:0xf bank_mask:0xf bound_ctrl:1
	v_pk_fma_f32 v[240:241], v[84:85], v[176:177], v[120:121]
	v_add_f32_dpp v92, v92, v92 row_ror:2 row_mask:0xf bank_mask:0xf bound_ctrl:1
	v_add_f32_dpp v118, v118, v118 row_ror:2 row_mask:0xf bank_mask:0xf bound_ctrl:1
	v_pk_fma_f32 v[242:243], v[86:87], v[178:179], v[238:239]
	v_add_f32_dpp v92, v92, v92 row_ror:1 row_mask:0xf bank_mask:0xf bound_ctrl:1
	v_add_f32_dpp v118, v118, v118 row_ror:1 row_mask:0xf bank_mask:0xf bound_ctrl:1
	v_pk_fma_f32 v[84:85], v[92:93], v[172:173], v[240:241] op_sel_hi:[0,1,1] neg_lo:[1,0,0] neg_hi:[1,0,0]
	v_pk_fma_f32 v[86:87], v[92:93], v[174:175], v[242:243] op_sel_hi:[0,1,1] neg_lo:[1,0,0] neg_hi:[1,0,0]
	v_fmac_f32_e32 v145, v135, v118
	ds_read_b128 v[56:59], v101 offset:12096
	ds_read_b128 v[60:63], v101 offset:12352
	ds_read_b128 v[64:67], v101 offset:12608
	ds_read_b128 v[68:71], v101 offset:12864
	ds_read_b128 v[72:75], v101 offset:13120
	s_waitcnt lgkmcnt(5)
	v_pk_mul_f32 v[88:89], v[84:85], v[36:37]
	v_pk_mul_f32 v[90:91], v[84:85], v[184:185]
	v_pk_fma_f32 v[88:89], v[86:87], v[38:39], v[88:89]
	v_pk_fma_f32 v[90:91], v[86:87], v[186:187], v[90:91]
	v_add_f32_e32 v92, v88, v89
	v_add_f32_e32 v118, v90, v91
	v_pk_mul_f32 v[120:121], v[48:49], v[76:77] op_sel:[0,0] op_sel_hi:[1,0]
	v_add_f32_dpp v92, v92, v92 row_ror:8 row_mask:0xf bank_mask:0xf bound_ctrl:1
	v_add_f32_dpp v118, v118, v118 row_ror:8 row_mask:0xf bank_mask:0xf bound_ctrl:1
	v_pk_mul_f32 v[238:239], v[50:51], v[76:77] op_sel:[0,0] op_sel_hi:[1,0]
	v_add_f32_dpp v92, v92, v92 row_ror:4 row_mask:0xf bank_mask:0xf bound_ctrl:1
	v_add_f32_dpp v118, v118, v118 row_ror:4 row_mask:0xf bank_mask:0xf bound_ctrl:1
	v_pk_fma_f32 v[240:241], v[84:85], v[44:45], v[120:121]
	v_add_f32_dpp v92, v92, v92 row_ror:2 row_mask:0xf bank_mask:0xf bound_ctrl:1
	v_add_f32_dpp v118, v118, v118 row_ror:2 row_mask:0xf bank_mask:0xf bound_ctrl:1
	v_pk_fma_f32 v[242:243], v[86:87], v[46:47], v[238:239]
	v_add_f32_dpp v92, v92, v92 row_ror:1 row_mask:0xf bank_mask:0xf bound_ctrl:1
	v_add_f32_dpp v118, v118, v118 row_ror:1 row_mask:0xf bank_mask:0xf bound_ctrl:1
	v_pk_fma_f32 v[84:85], v[92:93], v[40:41], v[240:241] op_sel_hi:[0,1,1] neg_lo:[1,0,0] neg_hi:[1,0,0]
	v_pk_fma_f32 v[86:87], v[92:93], v[42:43], v[242:243] op_sel_hi:[0,1,1] neg_lo:[1,0,0] neg_hi:[1,0,0]
	v_fmac_f32_e32 v145, v136, v118
	ds_read_b128 v[148:151], v101 offset:13440
	ds_read_b128 v[152:155], v101 offset:13696
	ds_read_b128 v[156:159], v101 offset:13952
	ds_read_b128 v[160:163], v101 offset:14208
	ds_read_b128 v[164:167], v101 offset:14464
	s_waitcnt lgkmcnt(5)
; #define LAS __attribute__((address_space(3)))
; __device__ __forceinline__ float allred16_dpp(float x) { x = dpp_add<0x128>(x); x = dpp_add<0x124>(x); x = dpp_add<0x122>(x); x = dpp_add<0x121>(x); return x; }
; __device__ __forceinline__ void scan_phase(const Args& a, LAS unsigned char* lds, int tid, int lane, int wave, int G, int bid) {
;     ...
;                     for (int i = 0; i < 16; ++i) {
;                         const f32x4 kk4 = nkk, ak4 = nak, w4 = nw, k4 = nk, r4 = nr; const float vv = vq[i >> 2][i & 3];
;                         { const int nx = (i < 15) ? (i + 1) : (oh < 1 ? 16 : 15); const LAS float* on = opb + nx * SC_STEP;
;                           nkk = *(const LAS f32x4*)(on); nak = *(const LAS f32x4*)(on + 64); nw = *(const LAS f32x4*)(on + 128); nk = *(const LAS f32x4*)(on + 192); nr = *(const LAS f32x4*)(on + 256); }
;                         f32x2 t = Sa * (f32x2){kk4[0], kk4[1]}; t = __builtin_elementwise_fma(Sb, (f32x2){kk4[2], kk4[3]}, t);
;                         float sa = t.x + t.y;
;                         sa = allred16_dpp(sa);
;                         const f32x2 nsa2 = (f32x2){-sa, -sa}, vv2 = (f32x2){vv, vv};
;                         f32x2 ua = vv2 * (f32x2){k4[0], k4[1]}, ub = vv2 * (f32x2){k4[2], k4[3]};
;                         ua = __builtin_elementwise_fma(nsa2, (f32x2){ak4[0], ak4[1]}, ua); ub = __builtin_elementwise_fma(nsa2, (f32x2){ak4[2], ak4[3]}, ub);
;                         Sa = __builtin_elementwise_fma(Sa, (f32x2){w4[0], w4[1]}, ua); Sb = __builtin_elementwise_fma(Sb, (f32x2){w4[2], w4[3]}, ub);
;                         f32x2 yy = Sa * (f32x2){r4[0], r4[1]}; yy = __builtin_elementwise_fma(Sb, (f32x2){r4[2], r4[3]}, yy);
;                         float y = yy.x + yy.y;
;                         y = allred16_dpp(y);
;                         yk = fmaf(wsel[i], y, yk);
	v_pk_mul_f32 v[88:89], v[84:85], v[56:57]
	v_pk_mul_f32 v[90:91], v[84:85], v[52:53]
	v_pk_fma_f32 v[88:89], v[86:87], v[58:59], v[88:89]
	v_pk_fma_f32 v[90:91], v[86:87], v[54:55], v[90:91]
	v_add_f32_e32 v92, v88, v89
	v_add_f32_e32 v118, v90, v91
	v_pk_mul_f32 v[120:121], v[68:69], v[76:77] op_sel:[0,1] op_sel_hi:[1,1]
	v_add_f32_dpp v92, v92, v92 row_ror:8 row_mask:0xf bank_mask:0xf bound_ctrl:1
	v_add_f32_dpp v118, v118, v118 row_ror:8 row_mask:0xf bank_mask:0xf bound_ctrl:1
	v_pk_mul_f32 v[238:239], v[70:71], v[76:77] op_sel:[0,1] op_sel_hi:[1,1]
	v_add_f32_dpp v92, v92, v92 row_ror:4 row_mask:0xf bank_mask:0xf bound_ctrl:1
	v_add_f32_dpp v118, v118, v118 row_ror:4 row_mask:0xf bank_mask:0xf bound_ctrl:1
	v_pk_fma_f32 v[240:241], v[84:85], v[64:65], v[120:121]
	v_add_f32_dpp v92, v92, v92 row_ror:2 row_mask:0xf bank_mask:0xf bound_ctrl:1
	v_add_f32_dpp v118, v118, v118 row_ror:2 row_mask:0xf bank_mask:0xf bound_ctrl:1
	v_pk_fma_f32 v[242:243], v[86:87], v[66:67], v[238:239]
	v_add_f32_dpp v92, v92, v92 row_ror:1 row_mask:0xf bank_mask:0xf bound_ctrl:1
	v_add_f32_dpp v118, v118, v118 row_ror:1 row_mask:0xf bank_mask:0xf bound_ctrl:1
	v_pk_fma_f32 v[84:85], v[92:93], v[60:61], v[240:241] op_sel_hi:[0,1,1] neg_lo:[1,0,0] neg_hi:[1,0,0]
	v_pk_fma_f32 v[86:87], v[92:93], v[62:63], v[242:243] op_sel_hi:[0,1,1] neg_lo:[1,0,0] neg_hi:[1,0,0]
	v_fmac_f32_e32 v145, v137, v118
	ds_read_b128 v[168:171], v101 offset:14784
	ds_read_b128 v[172:175], v101 offset:15040
	ds_read_b128 v[176:179], v101 offset:15296
	ds_read_b128 v[180:183], v101 offset:15552
	ds_read_b128 v[184:187], v101 offset:15808
	ds_read_b128 v[80:83], v103 offset:768
	s_waitcnt lgkmcnt(6)
	v_pk_mul_f32 v[88:89], v[84:85], v[148:149]
	v_pk_mul_f32 v[90:91], v[84:85], v[72:73]
	v_pk_fma_f32 v[88:89], v[86:87], v[150:151], v[88:89]
	v_pk_fma_f32 v[90:91], v[86:87], v[74:75], v[90:91]
	v_add_f32_e32 v92, v88, v89
	v_add_f32_e32 v118, v90, v91
	v_pk_mul_f32 v[120:121], v[160:161], v[78:79] op_sel:[0,0] op_sel_hi:[1,0]
	v_add_f32_dpp v92, v92, v92 row_ror:8 row_mask:0xf bank_mask:0xf bound_ctrl:1
	v_add_f32_dpp v118, v118, v118 row_ror:8 row_mask:0xf bank_mask:0xf bound_ctrl:1
	v_pk_mul_f32 v[238:239], v[162:163], v[78:79] op_sel:[0,0] op_sel_hi:[1,0]
	v_add_f32_dpp v92, v92, v92 row_ror:4 row_mask:0xf bank_mask:0xf bound_ctrl:1
	v_add_f32_dpp v118, v118, v118 row_ror:4 row_mask:0xf bank_mask:0xf bound_ctrl:1
	v_pk_fma_f32 v[240:241], v[84:85], v[156:157], v[120:121]
	v_add_f32_dpp v92, v92, v92 row_ror:2 row_mask:0xf bank_mask:0xf bound_ctrl:1
	v_add_f32_dpp v118, v118, v118 row_ror:2 row_mask:0xf bank_mask:0xf bound_ctrl:1
	v_pk_fma_f32 v[242:243], v[86:87], v[158:159], v[238:239]
	v_add_f32_dpp v92, v92, v92 row_ror:1 row_mask:0xf bank_mask:0xf bound_ctrl:1
	v_add_f32_dpp v118, v118, v118 row_ror:1 row_mask:0xf bank_mask:0xf bound_ctrl:1
	v_pk_fma_f32 v[84:85], v[92:93], v[152:153], v[240:241] op_sel_hi:[0,1,1] neg_lo:[1,0,0] neg_hi:[1,0,0]
	v_pk_fma_f32 v[86:87], v[92:93], v[154:155], v[242:243] op_sel_hi:[0,1,1] neg_lo:[1,0,0] neg_hi:[1,0,0]
	v_fmac_f32_e32 v145, v138, v118
	ds_read_b128 v[36:39], v101 offset:16128
	ds_read_b128 v[40:43], v101 offset:16384
	ds_read_b128 v[44:47], v101 offset:16640
	ds_read_b128 v[48:51], v101 offset:16896
	ds_read_b128 v[52:55], v101 offset:17152
	s_waitcnt lgkmcnt(6)
	v_pk_mul_f32 v[88:89], v[84:85], v[168:169]
	v_pk_mul_f32 v[90:91], v[84:85], v[164:165]
	v_pk_fma_f32 v[88:89], v[86:87], v[170:171], v[88:89]
	v_pk_fma_f32 v[90:91], v[86:87], v[166:167], v[90:91]
	v_add_f32_e32 v92, v88, v89
	v_add_f32_e32 v118, v90, v91
	v_pk_mul_f32 v[120:121], v[180:181], v[78:79] op_sel:[0,1] op_sel_hi:[1,1]
	v_add_f32_dpp v92, v92, v92 row_ror:8 row_mask:0xf bank_mask:0xf bound_ctrl:1
	v_add_f32_dpp v118, v118, v118 row_ror:8 row_mask:0xf bank_mask:0xf bound_ctrl:1
	v_pk_mul_f32 v[238:239], v[182:183], v[78:79] op_sel:[0,1] op_sel_hi:[1,1]
	v_add_f32_dpp v92, v92, v92 row_ror:4 row_mask:0xf bank_mask:0xf bound_ctrl:1
	v_add_f32_dpp v118, v118, v118 row_ror:4 row_mask:0xf bank_mask:0xf bound_ctrl:1
	v_pk_fma_f32 v[240:241], v[84:85], v[176:177], v[120:121]
	v_add_f32_dpp v92, v92, v92 row_ror:2 row_mask:0xf bank_mask:0xf bound_ctrl:1
	v_add_f32_dpp v118, v118, v118 row_ror:2 row_mask:0xf bank_mask:0xf bound_ctrl:1
	v_pk_fma_f32 v[242:243], v[86:87], v[178:179], v[238:239]
	v_add_f32_dpp v92, v92, v92 row_ror:1 row_mask:0xf bank_mask:0xf bound_ctrl:1
	v_add_f32_dpp v118, v118, v118 row_ror:1 row_mask:0xf bank_mask:0xf bound_ctrl:1
	v_pk_fma_f32 v[84:85], v[92:93], v[172:173], v[240:241] op_sel_hi:[0,1,1] neg_lo:[1,0,0] neg_hi:[1,0,0]
	v_pk_fma_f32 v[86:87], v[92:93], v[174:175], v[242:243] op_sel_hi:[0,1,1] neg_lo:[1,0,0] neg_hi:[1,0,0]
	v_fmac_f32_e32 v145, v139, v118
	ds_read_b128 v[56:59], v101 offset:17472
	ds_read_b128 v[60:63], v101 offset:17728
	ds_read_b128 v[64:67], v101 offset:17984
	ds_read_b128 v[68:71], v101 offset:18240
	ds_read_b128 v[72:75], v101 offset:18496
	s_waitcnt lgkmcnt(5)
; #define LAS __attribute__((address_space(3)))
; __device__ __forceinline__ float allred16_dpp(float x) { x = dpp_add<0x128>(x); x = dpp_add<0x124>(x); x = dpp_add<0x122>(x); x = dpp_add<0x121>(x); return x; }
; __device__ __forceinline__ void scan_phase(const Args& a, LAS unsigned char* lds, int tid, int lane, int wave, int G, int bid) {
;     ...
;                     for (int i = 0; i < 16; ++i) {
;                         const f32x4 kk4 = nkk, ak4 = nak, w4 = nw, k4 = nk, r4 = nr; const float vv = vq[i >> 2][i & 3];
;                         { const int nx = (i < 15) ? (i + 1) : (oh < 1 ? 16 : 15); const LAS float* on = opb + nx * SC_STEP;
;                           nkk = *(const LAS f32x4*)(on); nak = *(const LAS f32x4*)(on + 64); nw = *(const LAS f32x4*)(on + 128); nk = *(const LAS f32x4*)(on + 192); nr = *(const LAS f32x4*)(on + 256); }
;                         f32x2 t = Sa * (f32x2){kk4[0], kk4[1]}; t = __builtin_elementwise_fma(Sb, (f32x2){kk4[2], kk4[3]}, t);
;                         float sa = t.x + t.y;
;                         sa = allred16_dpp(sa);
;                         const f32x2 nsa2 = (f32x2){-sa, -sa}, vv2 = (f32x2){vv, vv};
;                         f32x2 ua = vv2 * (f32x2){k4[0], k4[1]}, ub = vv2 * (f32x2){k4[2], k4[3]};
;                         ua = __builtin_elementwise_fma(nsa2, (f32x2){ak4[0], ak4[1]}, ua); ub = __builtin_elementwise_fma(nsa2, (f32x2){ak4[2], ak4[3]}, ub);
;                         Sa = __builtin_elementwise_fma(Sa, (f32x2){w4[0], w4[1]}, ua); Sb = __builtin_elementwise_fma(Sb, (f32x2){w4[2], w4[3]}, ub);
;                         f32x2 yy = Sa * (f32x2){r4[0], r4[1]}; yy = __builtin_elementwise_fma(Sb, (f32x2){r4[2], r4[3]}, yy);
;                         float y = yy.x + yy.y;
;                         y = allred16_dpp(y);
;                         yk = fmaf(wsel[i], y, yk);
	v_pk_mul_f32 v[88:89], v[84:85], v[36:37]
	v_pk_mul_f32 v[90:91], v[84:85], v[184:185]
	v_pk_fma_f32 v[88:89], v[86:87], v[38:39], v[88:89]
	v_pk_fma_f32 v[90:91], v[86:87], v[186:187], v[90:91]
	v_add_f32_e32 v92, v88, v89
	v_add_f32_e32 v118, v90, v91
	v_pk_mul_f32 v[120:121], v[48:49], v[80:81] op_sel:[0,0] op_sel_hi:[1,0]
	v_add_f32_dpp v92, v92, v92 row_ror:8 row_mask:0xf bank_mask:0xf bound_ctrl:1
	v_add_f32_dpp v118, v118, v118 row_ror:8 row_mask:0xf bank_mask:0xf bound_ctrl:1
	v_pk_mul_f32 v[238:239], v[50:51], v[80:81] op_sel:[0,0] op_sel_hi:[1,0]
	v_add_f32_dpp v92, v92, v92 row_ror:4 row_mask:0xf bank_mask:0xf bound_ctrl:1
	v_add_f32_dpp v118, v118, v118 row_ror:4 row_mask:0xf bank_mask:0xf bound_ctrl:1
	v_pk_fma_f32 v[240:241], v[84:85], v[44:45], v[120:121]
	v_add_f32_dpp v92, v92, v92 row_ror:2 row_mask:0xf bank_mask:0xf bound_ctrl:1
	v_add_f32_dpp v118, v118, v118 row_ror:2 row_mask:0xf bank_mask:0xf bound_ctrl:1
	v_pk_fma_f32 v[242:243], v[86:87], v[46:47], v[238:239]
	v_add_f32_dpp v92, v92, v92 row_ror:1 row_mask:0xf bank_mask:0xf bound_ctrl:1
	v_add_f32_dpp v118, v118, v118 row_ror:1 row_mask:0xf bank_mask:0xf bound_ctrl:1
	v_pk_fma_f32 v[84:85], v[92:93], v[40:41], v[240:241] op_sel_hi:[0,1,1] neg_lo:[1,0,0] neg_hi:[1,0,0]
	v_pk_fma_f32 v[86:87], v[92:93], v[42:43], v[242:243] op_sel_hi:[0,1,1] neg_lo:[1,0,0] neg_hi:[1,0,0]
	v_fmac_f32_e32 v145, v140, v118
	ds_read_b128 v[148:151], v101 offset:18816
	ds_read_b128 v[152:155], v101 offset:19072
	ds_read_b128 v[156:159], v101 offset:19328
	ds_read_b128 v[160:163], v101 offset:19584
	ds_read_b128 v[164:167], v101 offset:19840
	s_waitcnt lgkmcnt(5)
	v_pk_mul_f32 v[88:89], v[84:85], v[56:57]
	v_pk_mul_f32 v[90:91], v[84:85], v[52:53]
	v_pk_fma_f32 v[88:89], v[86:87], v[58:59], v[88:89]
	v_pk_fma_f32 v[90:91], v[86:87], v[54:55], v[90:91]
	v_add_f32_e32 v92, v88, v89
	v_add_f32_e32 v118, v90, v91
	v_pk_mul_f32 v[120:121], v[68:69], v[80:81] op_sel:[0,1] op_sel_hi:[1,1]
	v_add_f32_dpp v92, v92, v92 row_ror:8 row_mask:0xf bank_mask:0xf bound_ctrl:1
	v_add_f32_dpp v118, v118, v118 row_ror:8 row_mask:0xf bank_mask:0xf bound_ctrl:1
	v_pk_mul_f32 v[238:239], v[70:71], v[80:81] op_sel:[0,1] op_sel_hi:[1,1]
	v_add_f32_dpp v92, v92, v92 row_ror:4 row_mask:0xf bank_mask:0xf bound_ctrl:1
	v_add_f32_dpp v118, v118, v118 row_ror:4 row_mask:0xf bank_mask:0xf bound_ctrl:1
	v_pk_fma_f32 v[240:241], v[84:85], v[64:65], v[120:121]
	v_add_f32_dpp v92, v92, v92 row_ror:2 row_mask:0xf bank_mask:0xf bound_ctrl:1
	v_add_f32_dpp v118, v118, v118 row_ror:2 row_mask:0xf bank_mask:0xf bound_ctrl:1
	v_pk_fma_f32 v[242:243], v[86:87], v[66:67], v[238:239]
	v_add_f32_dpp v92, v92, v92 row_ror:1 row_mask:0xf bank_mask:0xf bound_ctrl:1
	v_add_f32_dpp v118, v118, v118 row_ror:1 row_mask:0xf bank_mask:0xf bound_ctrl:1
	v_pk_fma_f32 v[84:85], v[92:93], v[60:61], v[240:241] op_sel_hi:[0,1,1] neg_lo:[1,0,0] neg_hi:[1,0,0]
	v_pk_fma_f32 v[86:87], v[92:93], v[62:63], v[242:243] op_sel_hi:[0,1,1] neg_lo:[1,0,0] neg_hi:[1,0,0]
	v_fmac_f32_e32 v145, v141, v118
	ds_read_b128 v[168:171], v101 offset:20160
	ds_read_b128 v[172:175], v101 offset:20416
	ds_read_b128 v[176:179], v101 offset:20672
	ds_read_b128 v[180:183], v101 offset:20928
	ds_read_b128 v[184:187], v101 offset:21184
	ds_read_b128 v[76:79], v103 offset:1024
	s_waitcnt lgkmcnt(6)
	v_pk_mul_f32 v[88:89], v[84:85], v[148:149]
	v_pk_mul_f32 v[90:91], v[84:85], v[72:73]
	v_pk_fma_f32 v[88:89], v[86:87], v[150:151], v[88:89]
	v_pk_fma_f32 v[90:91], v[86:87], v[74:75], v[90:91]
	v_add_f32_e32 v92, v88, v89
	v_add_f32_e32 v118, v90, v91
	v_pk_mul_f32 v[120:121], v[160:161], v[82:83] op_sel:[0,0] op_sel_hi:[1,0]
	v_add_f32_dpp v92, v92, v92 row_ror:8 row_mask:0xf bank_mask:0xf bound_ctrl:1
	v_add_f32_dpp v118, v118, v118 row_ror:8 row_mask:0xf bank_mask:0xf bound_ctrl:1
	v_pk_mul_f32 v[238:239], v[162:163], v[82:83] op_sel:[0,0] op_sel_hi:[1,0]
	v_add_f32_dpp v92, v92, v92 row_ror:4 row_mask:0xf bank_mask:0xf bound_ctrl:1
	v_add_f32_dpp v118, v118, v118 row_ror:4 row_mask:0xf bank_mask:0xf bound_ctrl:1
	v_pk_fma_f32 v[240:241], v[84:85], v[156:157], v[120:121]
	v_add_f32_dpp v92, v92, v92 row_ror:2 row_mask:0xf bank_mask:0xf bound_ctrl:1
	v_add_f32_dpp v118, v118, v118 row_ror:2 row_mask:0xf bank_mask:0xf bound_ctrl:1
	v_pk_fma_f32 v[242:243], v[86:87], v[158:159], v[238:239]
	v_add_f32_dpp v92, v92, v92 row_ror:1 row_mask:0xf bank_mask:0xf bound_ctrl:1
	v_add_f32_dpp v118, v118, v118 row_ror:1 row_mask:0xf bank_mask:0xf bound_ctrl:1
	v_pk_fma_f32 v[84:85], v[92:93], v[152:153], v[240:241] op_sel_hi:[0,1,1] neg_lo:[1,0,0] neg_hi:[1,0,0]
	v_pk_fma_f32 v[86:87], v[92:93], v[154:155], v[242:243] op_sel_hi:[0,1,1] neg_lo:[1,0,0] neg_hi:[1,0,0]
	v_fmac_f32_e32 v145, v142, v118
	ds_read_b128 v[36:39], v101 offset:21504
	ds_read_b128 v[40:43], v101 offset:21760
	ds_read_b128 v[44:47], v101 offset:22016
	ds_read_b128 v[48:51], v101 offset:22272
	ds_read_b128 v[52:55], v101 offset:22528
	s_waitcnt lgkmcnt(6)
; #define LAS __attribute__((address_space(3)))
; __device__ __forceinline__ float allred16_dpp(float x) { x = dpp_add<0x128>(x); x = dpp_add<0x124>(x); x = dpp_add<0x122>(x); x = dpp_add<0x121>(x); return x; }
; __device__ __forceinline__ void scan_phase(const Args& a, LAS unsigned char* lds, int tid, int lane, int wave, int G, int bid) {
;     ...
;                     for (int i = 0; i < 16; ++i) {
;                         const f32x4 kk4 = nkk, ak4 = nak, w4 = nw, k4 = nk, r4 = nr; const float vv = vq[i >> 2][i & 3];
;                         { const int nx = (i < 15) ? (i + 1) : (oh < 1 ? 16 : 15); const LAS float* on = opb + nx * SC_STEP;
;                           nkk = *(const LAS f32x4*)(on); nak = *(const LAS f32x4*)(on + 64); nw = *(const LAS f32x4*)(on + 128); nk = *(const LAS f32x4*)(on + 192); nr = *(const LAS f32x4*)(on + 256); }
;                         f32x2 t = Sa * (f32x2){kk4[0], kk4[1]}; t = __builtin_elementwise_fma(Sb, (f32x2){kk4[2], kk4[3]}, t);
;                         float sa = t.x + t.y;
;                         sa = allred16_dpp(sa);
;                         const f32x2 nsa2 = (f32x2){-sa, -sa}, vv2 = (f32x2){vv, vv};
;                         f32x2 ua = vv2 * (f32x2){k4[0], k4[1]}, ub = vv2 * (f32x2){k4[2], k4[3]};
;                         ua = __builtin_elementwise_fma(nsa2, (f32x2){ak4[0], ak4[1]}, ua); ub = __builtin_elementwise_fma(nsa2, (f32x2){ak4[2], ak4[3]}, ub);
;                         Sa = __builtin_elementwise_fma(Sa, (f32x2){w4[0], w4[1]}, ua); Sb = __builtin_elementwise_fma(Sb, (f32x2){w4[2], w4[3]}, ub);
;                         f32x2 yy = Sa * (f32x2){r4[0], r4[1]}; yy = __builtin_elementwise_fma(Sb, (f32x2){r4[2], r4[3]}, yy);
;                         float y = yy.x + yy.y;
;                         y = allred16_dpp(y);
;                         yk = fmaf(wsel[i], y, yk);
;                     }
;                     YB[(oh * 16 + c) * 16 + row] = yk;
	v_pk_mul_f32 v[88:89], v[84:85], v[168:169]
	v_pk_mul_f32 v[90:91], v[84:85], v[164:165]
	v_pk_fma_f32 v[88:89], v[86:87], v[170:171], v[88:89]
	v_pk_fma_f32 v[90:91], v[86:87], v[166:167], v[90:91]
	v_add_f32_e32 v92, v88, v89
	v_add_f32_e32 v118, v90, v91
	v_pk_mul_f32 v[120:121], v[180:181], v[82:83] op_sel:[0,1] op_sel_hi:[1,1]
	v_add_f32_dpp v92, v92, v92 row_ror:8 row_mask:0xf bank_mask:0xf bound_ctrl:1
	v_add_f32_dpp v118, v118, v118 row_ror:8 row_mask:0xf bank_mask:0xf bound_ctrl:1
	v_pk_mul_f32 v[238:239], v[182:183], v[82:83] op_sel:[0,1] op_sel_hi:[1,1]
	v_add_f32_dpp v92, v92, v92 row_ror:4 row_mask:0xf bank_mask:0xf bound_ctrl:1
	v_add_f32_dpp v118, v118, v118 row_ror:4 row_mask:0xf bank_mask:0xf bound_ctrl:1
	v_pk_fma_f32 v[240:241], v[84:85], v[176:177], v[120:121]
	v_add_f32_dpp v92, v92, v92 row_ror:2 row_mask:0xf bank_mask:0xf bound_ctrl:1
	v_add_f32_dpp v118, v118, v118 row_ror:2 row_mask:0xf bank_mask:0xf bound_ctrl:1
	v_pk_fma_f32 v[242:243], v[86:87], v[178:179], v[238:239]
	v_add_f32_dpp v92, v92, v92 row_ror:1 row_mask:0xf bank_mask:0xf bound_ctrl:1
	v_add_f32_dpp v118, v118, v118 row_ror:1 row_mask:0xf bank_mask:0xf bound_ctrl:1
	v_pk_fma_f32 v[84:85], v[92:93], v[172:173], v[240:241] op_sel_hi:[0,1,1] neg_lo:[1,0,0] neg_hi:[1,0,0]
	v_pk_fma_f32 v[86:87], v[92:93], v[174:175], v[242:243] op_sel_hi:[0,1,1] neg_lo:[1,0,0] neg_hi:[1,0,0]
	v_fmac_f32_e32 v145, v143, v118
	ds_read_b128 v[56:59], v101 offset:22848
	ds_read_b128 v[60:63], v101 offset:23104
	ds_read_b128 v[64:67], v101 offset:23360
	ds_read_b128 v[68:71], v101 offset:23616
	ds_read_b128 v[72:75], v101 offset:23872
	s_waitcnt lgkmcnt(5)
	v_pk_mul_f32 v[88:89], v[84:85], v[36:37]
	v_pk_mul_f32 v[90:91], v[84:85], v[184:185]
	v_pk_fma_f32 v[88:89], v[86:87], v[38:39], v[88:89]
	v_pk_fma_f32 v[90:91], v[86:87], v[186:187], v[90:91]
	v_add_f32_e32 v92, v88, v89
	v_add_f32_e32 v118, v90, v91
	v_pk_mul_f32 v[120:121], v[48:49], v[76:77] op_sel:[0,0] op_sel_hi:[1,0]
	v_add_f32_dpp v92, v92, v92 row_ror:8 row_mask:0xf bank_mask:0xf bound_ctrl:1
	v_add_f32_dpp v118, v118, v118 row_ror:8 row_mask:0xf bank_mask:0xf bound_ctrl:1
	v_pk_mul_f32 v[238:239], v[50:51], v[76:77] op_sel:[0,0] op_sel_hi:[1,0]
	v_add_f32_dpp v92, v92, v92 row_ror:4 row_mask:0xf bank_mask:0xf bound_ctrl:1
	v_add_f32_dpp v118, v118, v118 row_ror:4 row_mask:0xf bank_mask:0xf bound_ctrl:1
	v_pk_fma_f32 v[240:241], v[84:85], v[44:45], v[120:121]
	v_add_f32_dpp v92, v92, v92 row_ror:2 row_mask:0xf bank_mask:0xf bound_ctrl:1
	v_add_f32_dpp v118, v118, v118 row_ror:2 row_mask:0xf bank_mask:0xf bound_ctrl:1
	v_pk_fma_f32 v[242:243], v[86:87], v[46:47], v[238:239]
	v_add_f32_dpp v92, v92, v92 row_ror:1 row_mask:0xf bank_mask:0xf bound_ctrl:1
	v_add_f32_dpp v118, v118, v118 row_ror:1 row_mask:0xf bank_mask:0xf bound_ctrl:1
	v_pk_fma_f32 v[84:85], v[92:93], v[40:41], v[240:241] op_sel_hi:[0,1,1] neg_lo:[1,0,0] neg_hi:[1,0,0]
	v_pk_fma_f32 v[86:87], v[92:93], v[42:43], v[242:243] op_sel_hi:[0,1,1] neg_lo:[1,0,0] neg_hi:[1,0,0]
	v_fmac_f32_e32 v145, v144, v118
	ds_write_b32 v146, v145 offset:0
	ds_read_b128 v[148:151], v101 offset:24192
	ds_read_b128 v[152:155], v101 offset:24448
	ds_read_b128 v[156:159], v101 offset:24704
	ds_read_b128 v[160:163], v101 offset:24960
	ds_read_b128 v[164:167], v101 offset:25216
	s_waitcnt lgkmcnt(6)
	v_pk_mul_f32 v[88:89], v[84:85], v[56:57]
	v_pk_mul_f32 v[90:91], v[84:85], v[52:53]
	v_pk_fma_f32 v[88:89], v[86:87], v[58:59], v[88:89]
	v_pk_fma_f32 v[90:91], v[86:87], v[54:55], v[90:91]
	v_add_f32_e32 v92, v88, v89
	v_add_f32_e32 v118, v90, v91
	v_pk_mul_f32 v[120:121], v[68:69], v[76:77] op_sel:[0,1] op_sel_hi:[1,1]
	v_add_f32_dpp v92, v92, v92 row_ror:8 row_mask:0xf bank_mask:0xf bound_ctrl:1
	v_add_f32_dpp v118, v118, v118 row_ror:8 row_mask:0xf bank_mask:0xf bound_ctrl:1
	v_pk_mul_f32 v[238:239], v[70:71], v[76:77] op_sel:[0,1] op_sel_hi:[1,1]
	v_add_f32_dpp v92, v92, v92 row_ror:4 row_mask:0xf bank_mask:0xf bound_ctrl:1
	v_add_f32_dpp v118, v118, v118 row_ror:4 row_mask:0xf bank_mask:0xf bound_ctrl:1
	v_pk_fma_f32 v[240:241], v[84:85], v[64:65], v[120:121]
	v_add_f32_dpp v92, v92, v92 row_ror:2 row_mask:0xf bank_mask:0xf bound_ctrl:1
	v_add_f32_dpp v118, v118, v118 row_ror:2 row_mask:0xf bank_mask:0xf bound_ctrl:1
	v_pk_fma_f32 v[242:243], v[86:87], v[66:67], v[238:239]
	v_add_f32_dpp v92, v92, v92 row_ror:1 row_mask:0xf bank_mask:0xf bound_ctrl:1
	v_add_f32_dpp v118, v118, v118 row_ror:1 row_mask:0xf bank_mask:0xf bound_ctrl:1
	v_pk_fma_f32 v[84:85], v[92:93], v[60:61], v[240:241] op_sel_hi:[0,1,1] neg_lo:[1,0,0] neg_hi:[1,0,0]
	v_pk_fma_f32 v[86:87], v[92:93], v[62:63], v[242:243] op_sel_hi:[0,1,1] neg_lo:[1,0,0] neg_hi:[1,0,0]
	v_mul_f32_e32 v244, v127, v118
	ds_read_b128 v[168:171], v101 offset:25536
	ds_read_b128 v[172:175], v101 offset:25792
	ds_read_b128 v[176:179], v101 offset:26048
	ds_read_b128 v[180:183], v101 offset:26304
	ds_read_b128 v[184:187], v101 offset:26560
	ds_read_b128 v[80:83], v103 offset:1280
	s_waitcnt lgkmcnt(6)
; #define LAS __attribute__((address_space(3)))
; __device__ __forceinline__ float allred16_dpp(float x) { x = dpp_add<0x128>(x); x = dpp_add<0x124>(x); x = dpp_add<0x122>(x); x = dpp_add<0x121>(x); return x; }
; __device__ __forceinline__ void scan_phase(const Args& a, LAS unsigned char* lds, int tid, int lane, int wave, int G, int bid) {
;     ...
;                     for (int i = 0; i < 16; ++i) {
;                         const f32x4 kk4 = nkk, ak4 = nak, w4 = nw, k4 = nk, r4 = nr; const float vv = vq[i >> 2][i & 3];
;                         { const int nx = (i < 15) ? (i + 1) : (oh < 1 ? 16 : 15); const LAS float* on = opb + nx * SC_STEP;
;                           nkk = *(const LAS f32x4*)(on); nak = *(const LAS f32x4*)(on + 64); nw = *(const LAS f32x4*)(on + 128); nk = *(const LAS f32x4*)(on + 192); nr = *(const LAS f32x4*)(on + 256); }
;                         f32x2 t = Sa * (f32x2){kk4[0], kk4[1]}; t = __builtin_elementwise_fma(Sb, (f32x2){kk4[2], kk4[3]}, t);
;                         float sa = t.x + t.y;
;                         sa = allred16_dpp(sa);
;                         const f32x2 nsa2 = (f32x2){-sa, -sa}, vv2 = (f32x2){vv, vv};
;                         f32x2 ua = vv2 * (f32x2){k4[0], k4[1]}, ub = vv2 * (f32x2){k4[2], k4[3]};
;                         ua = __builtin_elementwise_fma(nsa2, (f32x2){ak4[0], ak4[1]}, ua); ub = __builtin_elementwise_fma(nsa2, (f32x2){ak4[2], ak4[3]}, ub);
;                         Sa = __builtin_elementwise_fma(Sa, (f32x2){w4[0], w4[1]}, ua); Sb = __builtin_elementwise_fma(Sb, (f32x2){w4[2], w4[3]}, ub);
;                         f32x2 yy = Sa * (f32x2){r4[0], r4[1]}; yy = __builtin_elementwise_fma(Sb, (f32x2){r4[2], r4[3]}, yy);
;                         float y = yy.x + yy.y;
;                         y = allred16_dpp(y);
;                         yk = fmaf(wsel[i], y, yk);
	v_pk_mul_f32 v[88:89], v[84:85], v[148:149]
	v_pk_mul_f32 v[90:91], v[84:85], v[72:73]
	v_pk_fma_f32 v[88:89], v[86:87], v[150:151], v[88:89]
	v_pk_fma_f32 v[90:91], v[86:87], v[74:75], v[90:91]
	v_add_f32_e32 v92, v88, v89
	v_add_f32_e32 v118, v90, v91
	v_pk_mul_f32 v[120:121], v[160:161], v[78:79] op_sel:[0,0] op_sel_hi:[1,0]
	v_add_f32_dpp v92, v92, v92 row_ror:8 row_mask:0xf bank_mask:0xf bound_ctrl:1
	v_add_f32_dpp v118, v118, v118 row_ror:8 row_mask:0xf bank_mask:0xf bound_ctrl:1
	v_pk_mul_f32 v[238:239], v[162:163], v[78:79] op_sel:[0,0] op_sel_hi:[1,0]
	v_add_f32_dpp v92, v92, v92 row_ror:4 row_mask:0xf bank_mask:0xf bound_ctrl:1
	v_add_f32_dpp v118, v118, v118 row_ror:4 row_mask:0xf bank_mask:0xf bound_ctrl:1
	v_pk_fma_f32 v[240:241], v[84:85], v[156:157], v[120:121]
	v_add_f32_dpp v92, v92, v92 row_ror:2 row_mask:0xf bank_mask:0xf bound_ctrl:1
	v_add_f32_dpp v118, v118, v118 row_ror:2 row_mask:0xf bank_mask:0xf bound_ctrl:1
	v_pk_fma_f32 v[242:243], v[86:87], v[158:159], v[238:239]
	v_add_f32_dpp v92, v92, v92 row_ror:1 row_mask:0xf bank_mask:0xf bound_ctrl:1
	v_add_f32_dpp v118, v118, v118 row_ror:1 row_mask:0xf bank_mask:0xf bound_ctrl:1
	v_pk_fma_f32 v[84:85], v[92:93], v[152:153], v[240:241] op_sel_hi:[0,1,1] neg_lo:[1,0,0] neg_hi:[1,0,0]
	v_pk_fma_f32 v[86:87], v[92:93], v[154:155], v[242:243] op_sel_hi:[0,1,1] neg_lo:[1,0,0] neg_hi:[1,0,0]
	v_fmac_f32_e32 v244, v129, v118
	ds_read_b128 v[36:39], v101 offset:26880
	ds_read_b128 v[40:43], v101 offset:27136
	ds_read_b128 v[44:47], v101 offset:27392
	ds_read_b128 v[48:51], v101 offset:27648
	ds_read_b128 v[52:55], v101 offset:27904
	s_waitcnt lgkmcnt(6)
	v_pk_mul_f32 v[88:89], v[84:85], v[168:169]
	v_pk_mul_f32 v[90:91], v[84:85], v[164:165]
	v_pk_fma_f32 v[88:89], v[86:87], v[170:171], v[88:89]
	v_pk_fma_f32 v[90:91], v[86:87], v[166:167], v[90:91]
	v_add_f32_e32 v92, v88, v89
	v_add_f32_e32 v118, v90, v91
	v_pk_mul_f32 v[120:121], v[180:181], v[78:79] op_sel:[0,1] op_sel_hi:[1,1]
	v_add_f32_dpp v92, v92, v92 row_ror:8 row_mask:0xf bank_mask:0xf bound_ctrl:1
	v_add_f32_dpp v118, v118, v118 row_ror:8 row_mask:0xf bank_mask:0xf bound_ctrl:1
	v_pk_mul_f32 v[238:239], v[182:183], v[78:79] op_sel:[0,1] op_sel_hi:[1,1]
	v_add_f32_dpp v92, v92, v92 row_ror:4 row_mask:0xf bank_mask:0xf bound_ctrl:1
	v_add_f32_dpp v118, v118, v118 row_ror:4 row_mask:0xf bank_mask:0xf bound_ctrl:1
	v_pk_fma_f32 v[240:241], v[84:85], v[176:177], v[120:121]
	v_add_f32_dpp v92, v92, v92 row_ror:2 row_mask:0xf bank_mask:0xf bound_ctrl:1
	v_add_f32_dpp v118, v118, v118 row_ror:2 row_mask:0xf bank_mask:0xf bound_ctrl:1
	v_pk_fma_f32 v[242:243], v[86:87], v[178:179], v[238:239]
	v_add_f32_dpp v92, v92, v92 row_ror:1 row_mask:0xf bank_mask:0xf bound_ctrl:1
	v_add_f32_dpp v118, v118, v118 row_ror:1 row_mask:0xf bank_mask:0xf bound_ctrl:1
	v_pk_fma_f32 v[84:85], v[92:93], v[172:173], v[240:241] op_sel_hi:[0,1,1] neg_lo:[1,0,0] neg_hi:[1,0,0]
	v_pk_fma_f32 v[86:87], v[92:93], v[174:175], v[242:243] op_sel_hi:[0,1,1] neg_lo:[1,0,0] neg_hi:[1,0,0]
	v_fmac_f32_e32 v244, v131, v118
	ds_read_b128 v[56:59], v101 offset:28224
	ds_read_b128 v[60:63], v101 offset:28480
	ds_read_b128 v[64:67], v101 offset:28736
	ds_read_b128 v[68:71], v101 offset:28992
	ds_read_b128 v[72:75], v101 offset:29248
	s_waitcnt lgkmcnt(5)
	v_pk_mul_f32 v[88:89], v[84:85], v[36:37]
	v_pk_mul_f32 v[90:91], v[84:85], v[184:185]
	v_pk_fma_f32 v[88:89], v[86:87], v[38:39], v[88:89]
	v_pk_fma_f32 v[90:91], v[86:87], v[186:187], v[90:91]
	v_add_f32_e32 v92, v88, v89
	v_add_f32_e32 v118, v90, v91
	v_pk_mul_f32 v[120:121], v[48:49], v[80:81] op_sel:[0,0] op_sel_hi:[1,0]
	v_add_f32_dpp v92, v92, v92 row_ror:8 row_mask:0xf bank_mask:0xf bound_ctrl:1
	v_add_f32_dpp v118, v118, v118 row_ror:8 row_mask:0xf bank_mask:0xf bound_ctrl:1
	v_pk_mul_f32 v[238:239], v[50:51], v[80:81] op_sel:[0,0] op_sel_hi:[1,0]
	v_add_f32_dpp v92, v92, v92 row_ror:4 row_mask:0xf bank_mask:0xf bound_ctrl:1
	v_add_f32_dpp v118, v118, v118 row_ror:4 row_mask:0xf bank_mask:0xf bound_ctrl:1
	v_pk_fma_f32 v[240:241], v[84:85], v[44:45], v[120:121]
	v_add_f32_dpp v92, v92, v92 row_ror:2 row_mask:0xf bank_mask:0xf bound_ctrl:1
	v_add_f32_dpp v118, v118, v118 row_ror:2 row_mask:0xf bank_mask:0xf bound_ctrl:1
	v_pk_fma_f32 v[242:243], v[86:87], v[46:47], v[238:239]
	v_add_f32_dpp v92, v92, v92 row_ror:1 row_mask:0xf bank_mask:0xf bound_ctrl:1
	v_add_f32_dpp v118, v118, v118 row_ror:1 row_mask:0xf bank_mask:0xf bound_ctrl:1
	v_pk_fma_f32 v[84:85], v[92:93], v[40:41], v[240:241] op_sel_hi:[0,1,1] neg_lo:[1,0,0] neg_hi:[1,0,0]
	v_pk_fma_f32 v[86:87], v[92:93], v[42:43], v[242:243] op_sel_hi:[0,1,1] neg_lo:[1,0,0] neg_hi:[1,0,0]
	v_fmac_f32_e32 v244, v132, v118
	ds_read_b128 v[148:151], v101 offset:29568
	ds_read_b128 v[152:155], v101 offset:29824
	ds_read_b128 v[156:159], v101 offset:30080
	ds_read_b128 v[160:163], v101 offset:30336
	ds_read_b128 v[164:167], v101 offset:30592
	s_waitcnt lgkmcnt(5)
; #define LAS __attribute__((address_space(3)))
; __device__ __forceinline__ float allred16_dpp(float x) { x = dpp_add<0x128>(x); x = dpp_add<0x124>(x); x = dpp_add<0x122>(x); x = dpp_add<0x121>(x); return x; }
; __device__ __forceinline__ void scan_phase(const Args& a, LAS unsigned char* lds, int tid, int lane, int wave, int G, int bid) {
;     ...
;                     for (int i = 0; i < 16; ++i) {
;                         const f32x4 kk4 = nkk, ak4 = nak, w4 = nw, k4 = nk, r4 = nr; const float vv = vq[i >> 2][i & 3];
;                         { const int nx = (i < 15) ? (i + 1) : (oh < 1 ? 16 : 15); const LAS float* on = opb + nx * SC_STEP;
;                           nkk = *(const LAS f32x4*)(on); nak = *(const LAS f32x4*)(on + 64); nw = *(const LAS f32x4*)(on + 128); nk = *(const LAS f32x4*)(on + 192); nr = *(const LAS f32x4*)(on + 256); }
;                         f32x2 t = Sa * (f32x2){kk4[0], kk4[1]}; t = __builtin_elementwise_fma(Sb, (f32x2){kk4[2], kk4[3]}, t);
;                         float sa = t.x + t.y;
;                         sa = allred16_dpp(sa);
;                         const f32x2 nsa2 = (f32x2){-sa, -sa}, vv2 = (f32x2){vv, vv};
;                         f32x2 ua = vv2 * (f32x2){k4[0], k4[1]}, ub = vv2 * (f32x2){k4[2], k4[3]};
;                         ua = __builtin_elementwise_fma(nsa2, (f32x2){ak4[0], ak4[1]}, ua); ub = __builtin_elementwise_fma(nsa2, (f32x2){ak4[2], ak4[3]}, ub);
;                         Sa = __builtin_elementwise_fma(Sa, (f32x2){w4[0], w4[1]}, ua); Sb = __builtin_elementwise_fma(Sb, (f32x2){w4[2], w4[3]}, ub);
;                         f32x2 yy = Sa * (f32x2){r4[0], r4[1]}; yy = __builtin_elementwise_fma(Sb, (f32x2){r4[2], r4[3]}, yy);
;                         float y = yy.x + yy.y;
;                         y = allred16_dpp(y);
;                         yk = fmaf(wsel[i], y, yk);
	v_pk_mul_f32 v[88:89], v[84:85], v[56:57]
	v_pk_mul_f32 v[90:91], v[84:85], v[52:53]
	v_pk_fma_f32 v[88:89], v[86:87], v[58:59], v[88:89]
	v_pk_fma_f32 v[90:91], v[86:87], v[54:55], v[90:91]
	v_add_f32_e32 v92, v88, v89
	v_add_f32_e32 v118, v90, v91
	v_pk_mul_f32 v[120:121], v[68:69], v[80:81] op_sel:[0,1] op_sel_hi:[1,1]
	v_add_f32_dpp v92, v92, v92 row_ror:8 row_mask:0xf bank_mask:0xf bound_ctrl:1
	v_add_f32_dpp v118, v118, v118 row_ror:8 row_mask:0xf bank_mask:0xf bound_ctrl:1
	v_pk_mul_f32 v[238:239], v[70:71], v[80:81] op_sel:[0,1] op_sel_hi:[1,1]
	v_add_f32_dpp v92, v92, v92 row_ror:4 row_mask:0xf bank_mask:0xf bound_ctrl:1
	v_add_f32_dpp v118, v118, v118 row_ror:4 row_mask:0xf bank_mask:0xf bound_ctrl:1
	v_pk_fma_f32 v[240:241], v[84:85], v[64:65], v[120:121]
	v_add_f32_dpp v92, v92, v92 row_ror:2 row_mask:0xf bank_mask:0xf bound_ctrl:1
	v_add_f32_dpp v118, v118, v118 row_ror:2 row_mask:0xf bank_mask:0xf bound_ctrl:1
	v_pk_fma_f32 v[242:243], v[86:87], v[66:67], v[238:239]
	v_add_f32_dpp v92, v92, v92 row_ror:1 row_mask:0xf bank_mask:0xf bound_ctrl:1
	v_add_f32_dpp v118, v118, v118 row_ror:1 row_mask:0xf bank_mask:0xf bound_ctrl:1
	v_pk_fma_f32 v[84:85], v[92:93], v[60:61], v[240:241] op_sel_hi:[0,1,1] neg_lo:[1,0,0] neg_hi:[1,0,0]
	v_pk_fma_f32 v[86:87], v[92:93], v[62:63], v[242:243] op_sel_hi:[0,1,1] neg_lo:[1,0,0] neg_hi:[1,0,0]
	v_fmac_f32_e32 v244, v133, v118
	ds_read_b128 v[168:171], v101 offset:30912
	ds_read_b128 v[172:175], v101 offset:31168
	ds_read_b128 v[176:179], v101 offset:31424
	ds_read_b128 v[180:183], v101 offset:31680
	ds_read_b128 v[184:187], v101 offset:31936
	ds_read_b128 v[76:79], v103 offset:1536
	s_waitcnt lgkmcnt(6)
	v_pk_mul_f32 v[88:89], v[84:85], v[148:149]
	v_pk_mul_f32 v[90:91], v[84:85], v[72:73]
	v_pk_fma_f32 v[88:89], v[86:87], v[150:151], v[88:89]
	v_pk_fma_f32 v[90:91], v[86:87], v[74:75], v[90:91]
	v_add_f32_e32 v92, v88, v89
	v_add_f32_e32 v118, v90, v91
	v_pk_mul_f32 v[120:121], v[160:161], v[82:83] op_sel:[0,0] op_sel_hi:[1,0]
	v_add_f32_dpp v92, v92, v92 row_ror:8 row_mask:0xf bank_mask:0xf bound_ctrl:1
	v_add_f32_dpp v118, v118, v118 row_ror:8 row_mask:0xf bank_mask:0xf bound_ctrl:1
	v_pk_mul_f32 v[238:239], v[162:163], v[82:83] op_sel:[0,0] op_sel_hi:[1,0]
	v_add_f32_dpp v92, v92, v92 row_ror:4 row_mask:0xf bank_mask:0xf bound_ctrl:1
	v_add_f32_dpp v118, v118, v118 row_ror:4 row_mask:0xf bank_mask:0xf bound_ctrl:1
	v_pk_fma_f32 v[240:241], v[84:85], v[156:157], v[120:121]
	v_add_f32_dpp v92, v92, v92 row_ror:2 row_mask:0xf bank_mask:0xf bound_ctrl:1
	v_add_f32_dpp v118, v118, v118 row_ror:2 row_mask:0xf bank_mask:0xf bound_ctrl:1
	v_pk_fma_f32 v[242:243], v[86:87], v[158:159], v[238:239]
	v_add_f32_dpp v92, v92, v92 row_ror:1 row_mask:0xf bank_mask:0xf bound_ctrl:1
	v_add_f32_dpp v118, v118, v118 row_ror:1 row_mask:0xf bank_mask:0xf bound_ctrl:1
	v_pk_fma_f32 v[84:85], v[92:93], v[152:153], v[240:241] op_sel_hi:[0,1,1] neg_lo:[1,0,0] neg_hi:[1,0,0]
	v_pk_fma_f32 v[86:87], v[92:93], v[154:155], v[242:243] op_sel_hi:[0,1,1] neg_lo:[1,0,0] neg_hi:[1,0,0]
	v_fmac_f32_e32 v244, v134, v118
	ds_read_b128 v[36:39], v101 offset:32256
	ds_read_b128 v[40:43], v101 offset:32512
	ds_read_b128 v[44:47], v101 offset:32768
	ds_read_b128 v[48:51], v101 offset:33024
	ds_read_b128 v[52:55], v101 offset:33280
	s_waitcnt lgkmcnt(6)
	v_pk_mul_f32 v[88:89], v[84:85], v[168:169]
	v_pk_mul_f32 v[90:91], v[84:85], v[164:165]
	v_pk_fma_f32 v[88:89], v[86:87], v[170:171], v[88:89]
	v_pk_fma_f32 v[90:91], v[86:87], v[166:167], v[90:91]
	v_add_f32_e32 v92, v88, v89
	v_add_f32_e32 v118, v90, v91
	v_pk_mul_f32 v[120:121], v[180:181], v[82:83] op_sel:[0,1] op_sel_hi:[1,1]
	v_add_f32_dpp v92, v92, v92 row_ror:8 row_mask:0xf bank_mask:0xf bound_ctrl:1
	v_add_f32_dpp v118, v118, v118 row_ror:8 row_mask:0xf bank_mask:0xf bound_ctrl:1
	v_pk_mul_f32 v[238:239], v[182:183], v[82:83] op_sel:[0,1] op_sel_hi:[1,1]
	v_add_f32_dpp v92, v92, v92 row_ror:4 row_mask:0xf bank_mask:0xf bound_ctrl:1
	v_add_f32_dpp v118, v118, v118 row_ror:4 row_mask:0xf bank_mask:0xf bound_ctrl:1
	v_pk_fma_f32 v[240:241], v[84:85], v[176:177], v[120:121]
	v_add_f32_dpp v92, v92, v92 row_ror:2 row_mask:0xf bank_mask:0xf bound_ctrl:1
	v_add_f32_dpp v118, v118, v118 row_ror:2 row_mask:0xf bank_mask:0xf bound_ctrl:1
	v_pk_fma_f32 v[242:243], v[86:87], v[178:179], v[238:239]
	v_add_f32_dpp v92, v92, v92 row_ror:1 row_mask:0xf bank_mask:0xf bound_ctrl:1
	v_add_f32_dpp v118, v118, v118 row_ror:1 row_mask:0xf bank_mask:0xf bound_ctrl:1
	v_pk_fma_f32 v[84:85], v[92:93], v[172:173], v[240:241] op_sel_hi:[0,1,1] neg_lo:[1,0,0] neg_hi:[1,0,0]
	v_pk_fma_f32 v[86:87], v[92:93], v[174:175], v[242:243] op_sel_hi:[0,1,1] neg_lo:[1,0,0] neg_hi:[1,0,0]
	v_fmac_f32_e32 v244, v135, v118
	ds_read_b128 v[56:59], v101 offset:33600
	ds_read_b128 v[60:63], v101 offset:33856
	ds_read_b128 v[64:67], v101 offset:34112
	ds_read_b128 v[68:71], v101 offset:34368
	ds_read_b128 v[72:75], v101 offset:34624
	s_waitcnt lgkmcnt(5)
; #define LAS __attribute__((address_space(3)))
; __device__ __forceinline__ float allred16_dpp(float x) { x = dpp_add<0x128>(x); x = dpp_add<0x124>(x); x = dpp_add<0x122>(x); x = dpp_add<0x121>(x); return x; }
; __device__ __forceinline__ void scan_phase(const Args& a, LAS unsigned char* lds, int tid, int lane, int wave, int G, int bid) {
;     ...
;                     for (int i = 0; i < 16; ++i) {
;                         const f32x4 kk4 = nkk, ak4 = nak, w4 = nw, k4 = nk, r4 = nr; const float vv = vq[i >> 2][i & 3];
;                         { const int nx = (i < 15) ? (i + 1) : (oh < 1 ? 16 : 15); const LAS float* on = opb + nx * SC_STEP;
;                           nkk = *(const LAS f32x4*)(on); nak = *(const LAS f32x4*)(on + 64); nw = *(const LAS f32x4*)(on + 128); nk = *(const LAS f32x4*)(on + 192); nr = *(const LAS f32x4*)(on + 256); }
;                         f32x2 t = Sa * (f32x2){kk4[0], kk4[1]}; t = __builtin_elementwise_fma(Sb, (f32x2){kk4[2], kk4[3]}, t);
;                         float sa = t.x + t.y;
;                         sa = allred16_dpp(sa);
;                         const f32x2 nsa2 = (f32x2){-sa, -sa}, vv2 = (f32x2){vv, vv};
;                         f32x2 ua = vv2 * (f32x2){k4[0], k4[1]}, ub = vv2 * (f32x2){k4[2], k4[3]};
;                         ua = __builtin_elementwise_fma(nsa2, (f32x2){ak4[0], ak4[1]}, ua); ub = __builtin_elementwise_fma(nsa2, (f32x2){ak4[2], ak4[3]}, ub);
;                         Sa = __builtin_elementwise_fma(Sa, (f32x2){w4[0], w4[1]}, ua); Sb = __builtin_elementwise_fma(Sb, (f32x2){w4[2], w4[3]}, ub);
;                         f32x2 yy = Sa * (f32x2){r4[0], r4[1]}; yy = __builtin_elementwise_fma(Sb, (f32x2){r4[2], r4[3]}, yy);
;                         float y = yy.x + yy.y;
;                         y = allred16_dpp(y);
;                         yk = fmaf(wsel[i], y, yk);
	v_pk_mul_f32 v[88:89], v[84:85], v[36:37]
	v_pk_mul_f32 v[90:91], v[84:85], v[184:185]
	v_pk_fma_f32 v[88:89], v[86:87], v[38:39], v[88:89]
	v_pk_fma_f32 v[90:91], v[86:87], v[186:187], v[90:91]
	v_add_f32_e32 v92, v88, v89
	v_add_f32_e32 v118, v90, v91
	v_pk_mul_f32 v[120:121], v[48:49], v[76:77] op_sel:[0,0] op_sel_hi:[1,0]
	v_add_f32_dpp v92, v92, v92 row_ror:8 row_mask:0xf bank_mask:0xf bound_ctrl:1
	v_add_f32_dpp v118, v118, v118 row_ror:8 row_mask:0xf bank_mask:0xf bound_ctrl:1
	v_pk_mul_f32 v[238:239], v[50:51], v[76:77] op_sel:[0,0] op_sel_hi:[1,0]
	v_add_f32_dpp v92, v92, v92 row_ror:4 row_mask:0xf bank_mask:0xf bound_ctrl:1
	v_add_f32_dpp v118, v118, v118 row_ror:4 row_mask:0xf bank_mask:0xf bound_ctrl:1
	v_pk_fma_f32 v[240:241], v[84:85], v[44:45], v[120:121]
	v_add_f32_dpp v92, v92, v92 row_ror:2 row_mask:0xf bank_mask:0xf bound_ctrl:1
	v_add_f32_dpp v118, v118, v118 row_ror:2 row_mask:0xf bank_mask:0xf bound_ctrl:1
	v_pk_fma_f32 v[242:243], v[86:87], v[46:47], v[238:239]
	v_add_f32_dpp v92, v92, v92 row_ror:1 row_mask:0xf bank_mask:0xf bound_ctrl:1
	v_add_f32_dpp v118, v118, v118 row_ror:1 row_mask:0xf bank_mask:0xf bound_ctrl:1
	v_pk_fma_f32 v[84:85], v[92:93], v[40:41], v[240:241] op_sel_hi:[0,1,1] neg_lo:[1,0,0] neg_hi:[1,0,0]
	v_pk_fma_f32 v[86:87], v[92:93], v[42:43], v[242:243] op_sel_hi:[0,1,1] neg_lo:[1,0,0] neg_hi:[1,0,0]
	v_fmac_f32_e32 v244, v136, v118
	ds_read_b128 v[148:151], v101 offset:34944
	ds_read_b128 v[152:155], v101 offset:35200
	ds_read_b128 v[156:159], v101 offset:35456
	ds_read_b128 v[160:163], v101 offset:35712
	ds_read_b128 v[164:167], v101 offset:35968
	s_waitcnt lgkmcnt(5)
	v_pk_mul_f32 v[88:89], v[84:85], v[56:57]
	v_pk_mul_f32 v[90:91], v[84:85], v[52:53]
	v_pk_fma_f32 v[88:89], v[86:87], v[58:59], v[88:89]
	v_pk_fma_f32 v[90:91], v[86:87], v[54:55], v[90:91]
	v_add_f32_e32 v92, v88, v89
	v_add_f32_e32 v118, v90, v91
	v_pk_mul_f32 v[120:121], v[68:69], v[76:77] op_sel:[0,1] op_sel_hi:[1,1]
	v_add_f32_dpp v92, v92, v92 row_ror:8 row_mask:0xf bank_mask:0xf bound_ctrl:1
	v_add_f32_dpp v118, v118, v118 row_ror:8 row_mask:0xf bank_mask:0xf bound_ctrl:1
	v_pk_mul_f32 v[238:239], v[70:71], v[76:77] op_sel:[0,1] op_sel_hi:[1,1]
	v_add_f32_dpp v92, v92, v92 row_ror:4 row_mask:0xf bank_mask:0xf bound_ctrl:1
	v_add_f32_dpp v118, v118, v118 row_ror:4 row_mask:0xf bank_mask:0xf bound_ctrl:1
	v_pk_fma_f32 v[240:241], v[84:85], v[64:65], v[120:121]
	v_add_f32_dpp v92, v92, v92 row_ror:2 row_mask:0xf bank_mask:0xf bound_ctrl:1
	v_add_f32_dpp v118, v118, v118 row_ror:2 row_mask:0xf bank_mask:0xf bound_ctrl:1
	v_pk_fma_f32 v[242:243], v[86:87], v[66:67], v[238:239]
	v_add_f32_dpp v92, v92, v92 row_ror:1 row_mask:0xf bank_mask:0xf bound_ctrl:1
	v_add_f32_dpp v118, v118, v118 row_ror:1 row_mask:0xf bank_mask:0xf bound_ctrl:1
	v_pk_fma_f32 v[84:85], v[92:93], v[60:61], v[240:241] op_sel_hi:[0,1,1] neg_lo:[1,0,0] neg_hi:[1,0,0]
	v_pk_fma_f32 v[86:87], v[92:93], v[62:63], v[242:243] op_sel_hi:[0,1,1] neg_lo:[1,0,0] neg_hi:[1,0,0]
	v_fmac_f32_e32 v244, v137, v118
	ds_read_b128 v[168:171], v101 offset:36288
	ds_read_b128 v[172:175], v101 offset:36544
	ds_read_b128 v[176:179], v101 offset:36800
	ds_read_b128 v[180:183], v101 offset:37056
	ds_read_b128 v[184:187], v101 offset:37312
	ds_read_b128 v[80:83], v103 offset:1792
	s_waitcnt lgkmcnt(6)
	v_pk_mul_f32 v[88:89], v[84:85], v[148:149]
	v_pk_mul_f32 v[90:91], v[84:85], v[72:73]
	v_pk_fma_f32 v[88:89], v[86:87], v[150:151], v[88:89]
	v_pk_fma_f32 v[90:91], v[86:87], v[74:75], v[90:91]
	v_add_f32_e32 v92, v88, v89
	v_add_f32_e32 v118, v90, v91
	v_pk_mul_f32 v[120:121], v[160:161], v[78:79] op_sel:[0,0] op_sel_hi:[1,0]
	v_add_f32_dpp v92, v92, v92 row_ror:8 row_mask:0xf bank_mask:0xf bound_ctrl:1
	v_add_f32_dpp v118, v118, v118 row_ror:8 row_mask:0xf bank_mask:0xf bound_ctrl:1
	v_pk_mul_f32 v[238:239], v[162:163], v[78:79] op_sel:[0,0] op_sel_hi:[1,0]
	v_add_f32_dpp v92, v92, v92 row_ror:4 row_mask:0xf bank_mask:0xf bound_ctrl:1
	v_add_f32_dpp v118, v118, v118 row_ror:4 row_mask:0xf bank_mask:0xf bound_ctrl:1
	v_pk_fma_f32 v[240:241], v[84:85], v[156:157], v[120:121]
	v_add_f32_dpp v92, v92, v92 row_ror:2 row_mask:0xf bank_mask:0xf bound_ctrl:1
	v_add_f32_dpp v118, v118, v118 row_ror:2 row_mask:0xf bank_mask:0xf bound_ctrl:1
	v_pk_fma_f32 v[242:243], v[86:87], v[158:159], v[238:239]
	v_add_f32_dpp v92, v92, v92 row_ror:1 row_mask:0xf bank_mask:0xf bound_ctrl:1
	v_add_f32_dpp v118, v118, v118 row_ror:1 row_mask:0xf bank_mask:0xf bound_ctrl:1
	v_pk_fma_f32 v[84:85], v[92:93], v[152:153], v[240:241] op_sel_hi:[0,1,1] neg_lo:[1,0,0] neg_hi:[1,0,0]
	v_pk_fma_f32 v[86:87], v[92:93], v[154:155], v[242:243] op_sel_hi:[0,1,1] neg_lo:[1,0,0] neg_hi:[1,0,0]
	v_fmac_f32_e32 v244, v138, v118
	ds_read_b128 v[36:39], v101 offset:37632
	ds_read_b128 v[40:43], v101 offset:37888
	ds_read_b128 v[44:47], v101 offset:38144
	ds_read_b128 v[48:51], v101 offset:38400
	ds_read_b128 v[52:55], v101 offset:38656
	s_waitcnt lgkmcnt(6)
; #define LAS __attribute__((address_space(3)))
; __device__ __forceinline__ float allred16_dpp(float x) { x = dpp_add<0x128>(x); x = dpp_add<0x124>(x); x = dpp_add<0x122>(x); x = dpp_add<0x121>(x); return x; }
; __device__ __forceinline__ void scan_phase(const Args& a, LAS unsigned char* lds, int tid, int lane, int wave, int G, int bid) {
;     ...
;                     for (int i = 0; i < 16; ++i) {
;                         const f32x4 kk4 = nkk, ak4 = nak, w4 = nw, k4 = nk, r4 = nr; const float vv = vq[i >> 2][i & 3];
;                         { const int nx = (i < 15) ? (i + 1) : (oh < 1 ? 16 : 15); const LAS float* on = opb + nx * SC_STEP;
;                           nkk = *(const LAS f32x4*)(on); nak = *(const LAS f32x4*)(on + 64); nw = *(const LAS f32x4*)(on + 128); nk = *(const LAS f32x4*)(on + 192); nr = *(const LAS f32x4*)(on + 256); }
;                         f32x2 t = Sa * (f32x2){kk4[0], kk4[1]}; t = __builtin_elementwise_fma(Sb, (f32x2){kk4[2], kk4[3]}, t);
;                         float sa = t.x + t.y;
;                         sa = allred16_dpp(sa);
;                         const f32x2 nsa2 = (f32x2){-sa, -sa}, vv2 = (f32x2){vv, vv};
;                         f32x2 ua = vv2 * (f32x2){k4[0], k4[1]}, ub = vv2 * (f32x2){k4[2], k4[3]};
;                         ua = __builtin_elementwise_fma(nsa2, (f32x2){ak4[0], ak4[1]}, ua); ub = __builtin_elementwise_fma(nsa2, (f32x2){ak4[2], ak4[3]}, ub);
;                         Sa = __builtin_elementwise_fma(Sa, (f32x2){w4[0], w4[1]}, ua); Sb = __builtin_elementwise_fma(Sb, (f32x2){w4[2], w4[3]}, ub);
;                         f32x2 yy = Sa * (f32x2){r4[0], r4[1]}; yy = __builtin_elementwise_fma(Sb, (f32x2){r4[2], r4[3]}, yy);
;                         float y = yy.x + yy.y;
;                         y = allred16_dpp(y);
;                         yk = fmaf(wsel[i], y, yk);
;                     }
	v_pk_mul_f32 v[88:89], v[84:85], v[168:169]
	v_pk_mul_f32 v[90:91], v[84:85], v[164:165]
	v_pk_fma_f32 v[88:89], v[86:87], v[170:171], v[88:89]
	v_pk_fma_f32 v[90:91], v[86:87], v[166:167], v[90:91]
	v_add_f32_e32 v92, v88, v89
	v_add_f32_e32 v118, v90, v91
	v_pk_mul_f32 v[120:121], v[180:181], v[78:79] op_sel:[0,1] op_sel_hi:[1,1]
	v_add_f32_dpp v92, v92, v92 row_ror:8 row_mask:0xf bank_mask:0xf bound_ctrl:1
	v_add_f32_dpp v118, v118, v118 row_ror:8 row_mask:0xf bank_mask:0xf bound_ctrl:1
	v_pk_mul_f32 v[238:239], v[182:183], v[78:79] op_sel:[0,1] op_sel_hi:[1,1]
	v_add_f32_dpp v92, v92, v92 row_ror:4 row_mask:0xf bank_mask:0xf bound_ctrl:1
	v_add_f32_dpp v118, v118, v118 row_ror:4 row_mask:0xf bank_mask:0xf bound_ctrl:1
	v_pk_fma_f32 v[240:241], v[84:85], v[176:177], v[120:121]
	v_add_f32_dpp v92, v92, v92 row_ror:2 row_mask:0xf bank_mask:0xf bound_ctrl:1
	v_add_f32_dpp v118, v118, v118 row_ror:2 row_mask:0xf bank_mask:0xf bound_ctrl:1
	v_pk_fma_f32 v[242:243], v[86:87], v[178:179], v[238:239]
	v_add_f32_dpp v92, v92, v92 row_ror:1 row_mask:0xf bank_mask:0xf bound_ctrl:1
	v_add_f32_dpp v118, v118, v118 row_ror:1 row_mask:0xf bank_mask:0xf bound_ctrl:1
	v_pk_fma_f32 v[84:85], v[92:93], v[172:173], v[240:241] op_sel_hi:[0,1,1] neg_lo:[1,0,0] neg_hi:[1,0,0]
	v_pk_fma_f32 v[86:87], v[92:93], v[174:175], v[242:243] op_sel_hi:[0,1,1] neg_lo:[1,0,0] neg_hi:[1,0,0]
	v_fmac_f32_e32 v244, v139, v118
	ds_read_b128 v[56:59], v101 offset:38976
	ds_read_b128 v[60:63], v101 offset:39232
	ds_read_b128 v[64:67], v101 offset:39488
	ds_read_b128 v[68:71], v101 offset:39744
	ds_read_b128 v[72:75], v101 offset:40000
	s_waitcnt lgkmcnt(5)
	v_pk_mul_f32 v[88:89], v[84:85], v[36:37]
	v_pk_mul_f32 v[90:91], v[84:85], v[184:185]
	v_pk_fma_f32 v[88:89], v[86:87], v[38:39], v[88:89]
	v_pk_fma_f32 v[90:91], v[86:87], v[186:187], v[90:91]
	v_add_f32_e32 v92, v88, v89
	v_add_f32_e32 v118, v90, v91
	v_pk_mul_f32 v[120:121], v[48:49], v[80:81] op_sel:[0,0] op_sel_hi:[1,0]
	v_add_f32_dpp v92, v92, v92 row_ror:8 row_mask:0xf bank_mask:0xf bound_ctrl:1
	v_add_f32_dpp v118, v118, v118 row_ror:8 row_mask:0xf bank_mask:0xf bound_ctrl:1
	v_pk_mul_f32 v[238:239], v[50:51], v[80:81] op_sel:[0,0] op_sel_hi:[1,0]
	v_add_f32_dpp v92, v92, v92 row_ror:4 row_mask:0xf bank_mask:0xf bound_ctrl:1
	v_add_f32_dpp v118, v118, v118 row_ror:4 row_mask:0xf bank_mask:0xf bound_ctrl:1
	v_pk_fma_f32 v[240:241], v[84:85], v[44:45], v[120:121]
	v_add_f32_dpp v92, v92, v92 row_ror:2 row_mask:0xf bank_mask:0xf bound_ctrl:1
	v_add_f32_dpp v118, v118, v118 row_ror:2 row_mask:0xf bank_mask:0xf bound_ctrl:1
	v_pk_fma_f32 v[242:243], v[86:87], v[46:47], v[238:239]
	v_add_f32_dpp v92, v92, v92 row_ror:1 row_mask:0xf bank_mask:0xf bound_ctrl:1
	v_add_f32_dpp v118, v118, v118 row_ror:1 row_mask:0xf bank_mask:0xf bound_ctrl:1
	v_pk_fma_f32 v[84:85], v[92:93], v[40:41], v[240:241] op_sel_hi:[0,1,1] neg_lo:[1,0,0] neg_hi:[1,0,0]
	v_pk_fma_f32 v[86:87], v[92:93], v[42:43], v[242:243] op_sel_hi:[0,1,1] neg_lo:[1,0,0] neg_hi:[1,0,0]
	v_fmac_f32_e32 v244, v140, v118
	ds_read_b128 v[148:151], v101 offset:40320
	ds_read_b128 v[152:155], v101 offset:40576
	ds_read_b128 v[156:159], v101 offset:40832
	ds_read_b128 v[160:163], v101 offset:41088
	ds_read_b128 v[164:167], v101 offset:41344
	s_waitcnt lgkmcnt(5)
	s_barrier
	v_pk_mul_f32 v[88:89], v[84:85], v[56:57]
	v_pk_mul_f32 v[90:91], v[84:85], v[52:53]
	v_pk_fma_f32 v[88:89], v[86:87], v[58:59], v[88:89]
	v_pk_fma_f32 v[90:91], v[86:87], v[54:55], v[90:91]
	v_add_f32_e32 v92, v88, v89
	v_add_f32_e32 v118, v90, v91
	v_pk_mul_f32 v[120:121], v[68:69], v[80:81] op_sel:[0,1] op_sel_hi:[1,1]
	v_add_f32_dpp v92, v92, v92 row_ror:8 row_mask:0xf bank_mask:0xf bound_ctrl:1
	v_add_f32_dpp v118, v118, v118 row_ror:8 row_mask:0xf bank_mask:0xf bound_ctrl:1
	v_pk_mul_f32 v[238:239], v[70:71], v[80:81] op_sel:[0,1] op_sel_hi:[1,1]
	v_add_f32_dpp v92, v92, v92 row_ror:4 row_mask:0xf bank_mask:0xf bound_ctrl:1
	v_add_f32_dpp v118, v118, v118 row_ror:4 row_mask:0xf bank_mask:0xf bound_ctrl:1
	v_pk_fma_f32 v[240:241], v[84:85], v[64:65], v[120:121]
	v_add_f32_dpp v92, v92, v92 row_ror:2 row_mask:0xf bank_mask:0xf bound_ctrl:1
	v_add_f32_dpp v118, v118, v118 row_ror:2 row_mask:0xf bank_mask:0xf bound_ctrl:1
	v_pk_fma_f32 v[242:243], v[86:87], v[66:67], v[238:239]
	v_add_f32_dpp v92, v92, v92 row_ror:1 row_mask:0xf bank_mask:0xf bound_ctrl:1
	v_add_f32_dpp v118, v118, v118 row_ror:1 row_mask:0xf bank_mask:0xf bound_ctrl:1
	v_pk_fma_f32 v[84:85], v[92:93], v[60:61], v[240:241] op_sel_hi:[0,1,1] neg_lo:[1,0,0] neg_hi:[1,0,0]
	v_pk_fma_f32 v[86:87], v[92:93], v[62:63], v[242:243] op_sel_hi:[0,1,1] neg_lo:[1,0,0] neg_hi:[1,0,0]
	v_fmac_f32_e32 v244, v141, v118
	ds_read_b128 v[168:171], v101 offset:41664
	ds_read_b128 v[172:175], v101 offset:41920
	ds_read_b128 v[176:179], v101 offset:42176
	ds_read_b128 v[180:183], v101 offset:42432
	ds_read_b128 v[184:187], v101 offset:42688
	ds_read_b128 v[76:79], v124
	s_waitcnt lgkmcnt(6)
; #define LAS __attribute__((address_space(3)))
; __device__ __forceinline__ float bf_lo(unsigned u) { return __uint_as_float(u << 16); }
; __device__ __forceinline__ void scan_phase(const Args& a, LAS unsigned char* lds, int tid, int lane, int wave, int G, int bid) {
;     ...
;             if (stager) { SCAN_PUT8(buf + ldP, rKK); SCAN_PUT8(buf + ldP + 64, rAK); SCAN_PUT8(buf + ldP + 192, rK); SCAN_PUT8(buf + ldP + 256, rR);
;                 *(LAS f32x4*)(buf + ldD) = rD0; *(LAS f32x4*)(buf + ldD + 16 * SC_STEP) = rD1;
;                 if (sid < 64) { LAS float* vd = VV + (ch & 1) * 512 + (vst >> 2) * 64 + (vhalf * 8) * 4 + (vst & 3); vd[0] = bf_lo(rV.x); vd[4] = bf_hi(rV.x); vd[8] = bf_lo(rV.y); vd[12] = bf_hi(rV.y); vd[16] = bf_lo(rV.z); vd[20] = bf_hi(rV.z); vd[24] = bf_lo(rV.w); vd[28] = bf_hi(rV.w); } }
;     ...
;                     for (int i = 0; i < 16; ++i) {
;                         const f32x4 kk4 = nkk, ak4 = nak, w4 = nw, k4 = nk, r4 = nr; const float vv = vq[i >> 2][i & 3];
;                         { const int nx = (i < 15) ? (i + 1) : (oh < 1 ? 16 : 15); const LAS float* on = opb + nx * SC_STEP;
;                           nkk = *(const LAS f32x4*)(on); nak = *(const LAS f32x4*)(on + 64); nw = *(const LAS f32x4*)(on + 128); nk = *(const LAS f32x4*)(on + 192); nr = *(const LAS f32x4*)(on + 256); }
;                         f32x2 t = Sa * (f32x2){kk4[0], kk4[1]}; t = __builtin_elementwise_fma(Sb, (f32x2){kk4[2], kk4[3]}, t);
;                         float sa = t.x + t.y;
;                         sa = allred16_dpp(sa);
;                         const f32x2 nsa2 = (f32x2){-sa, -sa}, vv2 = (f32x2){vv, vv};
;                         f32x2 ua = vv2 * (f32x2){k4[0], k4[1]}, ub = vv2 * (f32x2){k4[2], k4[3]};
;                         ua = __builtin_elementwise_fma(nsa2, (f32x2){ak4[0], ak4[1]}, ua); ub = __builtin_elementwise_fma(nsa2, (f32x2){ak4[2], ak4[3]}, ub);
;                         Sa = __builtin_elementwise_fma(Sa, (f32x2){w4[0], w4[1]}, ua); Sb = __builtin_elementwise_fma(Sb, (f32x2){w4[2], w4[3]}, ub);
;                         f32x2 yy = Sa * (f32x2){r4[0], r4[1]}; yy = __builtin_elementwise_fma(Sb, (f32x2){r4[2], r4[3]}, yy);
;                         float y = yy.x + yy.y;
;                         y = allred16_dpp(y);
;                         yk = fmaf(wsel[i], y, yk);
;                     }
	v_pk_mul_f32 v[88:89], v[84:85], v[148:149]
	v_pk_mul_f32 v[90:91], v[84:85], v[72:73]
	v_pk_fma_f32 v[88:89], v[86:87], v[150:151], v[88:89]
	v_pk_fma_f32 v[90:91], v[86:87], v[74:75], v[90:91]
	v_add_f32_e32 v92, v88, v89
	v_add_f32_e32 v118, v90, v91
	v_pk_mul_f32 v[120:121], v[160:161], v[82:83] op_sel:[0,0] op_sel_hi:[1,0]
	v_add_f32_dpp v92, v92, v92 row_ror:8 row_mask:0xf bank_mask:0xf bound_ctrl:1
	v_add_f32_dpp v118, v118, v118 row_ror:8 row_mask:0xf bank_mask:0xf bound_ctrl:1
	v_pk_mul_f32 v[238:239], v[162:163], v[82:83] op_sel:[0,0] op_sel_hi:[1,0]
	v_add_f32_dpp v92, v92, v92 row_ror:4 row_mask:0xf bank_mask:0xf bound_ctrl:1
	v_add_f32_dpp v118, v118, v118 row_ror:4 row_mask:0xf bank_mask:0xf bound_ctrl:1
	v_pk_fma_f32 v[240:241], v[84:85], v[156:157], v[120:121]
	v_add_f32_dpp v92, v92, v92 row_ror:2 row_mask:0xf bank_mask:0xf bound_ctrl:1
	v_add_f32_dpp v118, v118, v118 row_ror:2 row_mask:0xf bank_mask:0xf bound_ctrl:1
	v_pk_fma_f32 v[242:243], v[86:87], v[158:159], v[238:239]
	v_add_f32_dpp v92, v92, v92 row_ror:1 row_mask:0xf bank_mask:0xf bound_ctrl:1
	v_add_f32_dpp v118, v118, v118 row_ror:1 row_mask:0xf bank_mask:0xf bound_ctrl:1
	v_pk_fma_f32 v[84:85], v[92:93], v[152:153], v[240:241] op_sel_hi:[0,1,1] neg_lo:[1,0,0] neg_hi:[1,0,0]
	v_pk_fma_f32 v[86:87], v[92:93], v[154:155], v[242:243] op_sel_hi:[0,1,1] neg_lo:[1,0,0] neg_hi:[1,0,0]
	v_fmac_f32_e32 v244, v142, v118
	ds_read_b128 v[36:39], v122
	ds_read_b128 v[40:43], v122 offset:256
	ds_read_b128 v[44:47], v122 offset:512
	ds_read_b128 v[48:51], v122 offset:768
	ds_read_b128 v[52:55], v122 offset:1024
	s_waitcnt lgkmcnt(6)
	v_pk_mul_f32 v[88:89], v[84:85], v[168:169]
	v_pk_mul_f32 v[90:91], v[84:85], v[164:165]
	v_pk_fma_f32 v[88:89], v[86:87], v[170:171], v[88:89]
	v_pk_fma_f32 v[90:91], v[86:87], v[166:167], v[90:91]
	v_add_f32_e32 v92, v88, v89
	v_add_f32_e32 v118, v90, v91
	v_pk_mul_f32 v[120:121], v[180:181], v[82:83] op_sel:[0,1] op_sel_hi:[1,1]
	v_add_f32_dpp v92, v92, v92 row_ror:8 row_mask:0xf bank_mask:0xf bound_ctrl:1
	v_add_f32_dpp v118, v118, v118 row_ror:8 row_mask:0xf bank_mask:0xf bound_ctrl:1
	v_pk_mul_f32 v[238:239], v[182:183], v[82:83] op_sel:[0,1] op_sel_hi:[1,1]
	v_add_f32_dpp v92, v92, v92 row_ror:4 row_mask:0xf bank_mask:0xf bound_ctrl:1
	v_add_f32_dpp v118, v118, v118 row_ror:4 row_mask:0xf bank_mask:0xf bound_ctrl:1
	v_pk_fma_f32 v[240:241], v[84:85], v[176:177], v[120:121]
	v_add_f32_dpp v92, v92, v92 row_ror:2 row_mask:0xf bank_mask:0xf bound_ctrl:1
	v_add_f32_dpp v118, v118, v118 row_ror:2 row_mask:0xf bank_mask:0xf bound_ctrl:1
	v_pk_fma_f32 v[242:243], v[86:87], v[178:179], v[238:239]
	v_add_f32_dpp v92, v92, v92 row_ror:1 row_mask:0xf bank_mask:0xf bound_ctrl:1
	v_add_f32_dpp v118, v118, v118 row_ror:1 row_mask:0xf bank_mask:0xf bound_ctrl:1
	v_pk_fma_f32 v[84:85], v[92:93], v[172:173], v[240:241] op_sel_hi:[0,1,1] neg_lo:[1,0,0] neg_hi:[1,0,0]
	v_pk_fma_f32 v[86:87], v[92:93], v[174:175], v[242:243] op_sel_hi:[0,1,1] neg_lo:[1,0,0] neg_hi:[1,0,0]
	v_fmac_f32_e32 v244, v143, v118
	ds_read_b128 v[56:59], v122 offset:1344
	ds_read_b128 v[60:63], v122 offset:1600
	ds_read_b128 v[64:67], v122 offset:1856
	ds_read_b128 v[68:71], v122 offset:2112
	ds_read_b128 v[72:75], v122 offset:2368
	v_mov_b32_e32 v126, v146
	v_mov_b32_e32 v101, v122
	v_mov_b32_e32 v103, v124
	v_lshl_add_u32 v146, s15, 11, v123
	s_branch .Lsp_next
.Lsp_stage:
	s_barrier
	s_cmpk_eq_i32 s54, 0x7f
	s_cbranch_scc1 .Lsp_flush
	s_add_i32 s55, s54, 1
	s_and_b32 s15, s55, 1
	s_mul_i32 s23, s15, 0xa800
	v_lshlrev_b32_e32 v40, 2, v96
	s_waitcnt vmcnt(0)
	v_add3_u32 v40, s23, v3, v40
	v_lshlrev_b32_e32 v36, 16, v12
	v_and_b32_e32 v37, 0xffff0000, v12
	v_lshlrev_b32_e32 v38, 16, v13
	v_and_b32_e32 v39, 0xffff0000, v13
	ds_write_b128 v40, v[36:39]
	v_lshlrev_b32_e32 v36, 16, v14
	v_and_b32_e32 v37, 0xffff0000, v14
	v_lshlrev_b32_e32 v38, 16, v15
	v_and_b32_e32 v39, 0xffff0000, v15
	ds_write_b128 v40, v[36:39] offset:16
	v_lshlrev_b32_e32 v36, 16, v16
	v_and_b32_e32 v37, 0xffff0000, v16
	v_lshlrev_b32_e32 v38, 16, v17
	v_and_b32_e32 v39, 0xffff0000, v17
	ds_write_b128 v40, v[36:39] offset:256
	v_lshlrev_b32_e32 v36, 16, v18
	v_and_b32_e32 v37, 0xffff0000, v18
	v_lshlrev_b32_e32 v38, 16, v19
	v_and_b32_e32 v39, 0xffff0000, v19
	ds_write_b128 v40, v[36:39] offset:272
	v_lshlrev_b32_e32 v36, 16, v20
	v_and_b32_e32 v37, 0xffff0000, v20
	v_lshlrev_b32_e32 v38, 16, v21
	v_and_b32_e32 v39, 0xffff0000, v21
	ds_write_b128 v40, v[36:39] offset:768
	v_lshlrev_b32_e32 v36, 16, v22
	v_and_b32_e32 v37, 0xffff0000, v22
	v_lshlrev_b32_e32 v38, 16, v23
	v_and_b32_e32 v39, 0xffff0000, v23
	ds_write_b128 v40, v[36:39] offset:784
	v_lshlrev_b32_e32 v36, 16, v24
	v_and_b32_e32 v37, 0xffff0000, v24
	v_lshlrev_b32_e32 v38, 16, v25
	v_and_b32_e32 v39, 0xffff0000, v25
	ds_write_b128 v40, v[36:39] offset:1024
	v_lshlrev_b32_e32 v36, 16, v26
	v_and_b32_e32 v37, 0xffff0000, v26
	v_lshlrev_b32_e32 v38, 16, v27
	v_and_b32_e32 v39, 0xffff0000, v27
	ds_write_b128 v40, v[36:39] offset:1040
	v_add3_u32 v36, s23, v95, v0
	ds_write_b128 v36, v[28:31] offset:512
	ds_write_b128 v36, v[32:35] offset:22016
	s_and_saveexec_b64 s[50:51], s[42:43]
	s_cbranch_execz .Lsp_l1
	v_lshl_add_u32 v36, s15, 11, v97
	v_lshlrev_b32_e32 v37, 16, v8
	v_and_b32_e32 v38, 0xffff0000, v8
	ds_write2_b32 v36, v37, v38 offset1:4
	v_lshlrev_b32_e32 v37, 16, v9
	v_and_b32_e32 v38, 0xffff0000, v9
	ds_write2_b32 v36, v37, v38 offset0:8 offset1:12
	v_lshlrev_b32_e32 v37, 16, v10
	v_and_b32_e32 v38, 0xffff0000, v10
	ds_write2_b32 v36, v37, v38 offset0:16 offset1:20
	v_lshlrev_b32_e32 v37, 16, v11
	v_and_b32_e32 v38, 0xffff0000, v11
	ds_write2_b32 v36, v37, v38 offset0:24 offset1:28

; #define LAS __attribute__((address_space(3)))
; __device__ __forceinline__ void scan_phase(const Args& a, LAS unsigned char* lds, int tid, int lane, int wave, int G, int bid) {
;     ...
;                     YB[(oh * 16 + c) * 16 + row] = yk;
;                 }
;             }
;             __syncthreads();
;             if (stager) { const int st = sid >> 3, r2 = (sid & 7) * 2; const f32x2 yv = *(const LAS f32x2*)(YB + st * 16 + r2); *(f32x2*)(YR + (tb + (size_t)ch * SC_CH + st) * 256 + h * 64 + v0 + r2) = yv; }
.Lsp_flush:
	s_cmp_eq_u32 s54, 0
	s_cbranch_scc1 .Lsp_noflush
	s_add_i32 s50, s54, -1
	s_and_b32 s51, s50, 1
	s_waitcnt lgkmcnt(0)
	v_lshl_add_u32 v38, s51, 11, v125
	ds_read_b64 v[38:39], v38
	v_lshl_or_b32 v36, s50, 5, v2
	v_or_b32_e32 v36, s48, v36
	v_mov_b32_e32 v37, s49
	v_lshlrev_b64 v[36:37], 10, v[36:37]
	v_lshl_add_u64 v[36:37], v[116:117], 0, v[36:37]
	s_waitcnt lgkmcnt(0)
	global_store_dwordx2 v[36:37], v[38:39], off
.Lsp_noflush:
	s_cmpk_gt_i32 s54, 0x7d
	s_cbranch_scc1 .Lsp_sdone
	s_add_i32 s55, s54, 2
	s_waitcnt lgkmcnt(0)
	s_lshl_b32 s96, s55, 13
	v_lshl_add_u64 v[28:29], s[96:97], 2, v[104:105]
	s_lshl_b32 s50, s55, 14
	s_mov_b32 s51, s97
	v_add_co_u32_e32 v32, vcc, 0x4000, v28
	v_lshl_add_u64 v[12:13], v[108:109], 0, s[50:51]
	v_lshl_add_u64 v[16:17], v[110:111], 0, s[50:51]
	v_lshl_add_u64 v[20:21], v[112:113], 0, s[50:51]
	v_lshl_add_u64 v[24:25], v[114:115], 0, s[50:51]
	v_addc_co_u32_e32 v33, vcc, 0, v29, vcc
	global_load_dwordx4 v[12:15], v[12:13], off
	s_nop 0
	global_load_dwordx4 v[16:19], v[16:17], off
	s_nop 0
	global_load_dwordx4 v[20:23], v[20:21], off
	s_nop 0
	global_load_dwordx4 v[24:27], v[24:25], off
	s_nop 0
	global_load_dwordx4 v[28:31], v[28:29], off
	s_nop 0
	global_load_dwordx4 v[32:35], v[32:33], off
	s_and_saveexec_b64 s[50:51], s[42:43]
	s_cbranch_execz .Lsp_l2
	s_lshl_b32 s96, s96, 1
	v_lshl_add_u64 v[8:9], v[106:107], 0, s[96:97]
	global_load_dwordx4 v[8:11], v[8:9], off

; #define LAS __attribute__((address_space(3)))
; __device__ __forceinline__ float allred16_dpp(float x) { x = dpp_add<0x128>(x); x = dpp_add<0x124>(x); x = dpp_add<0x122>(x); x = dpp_add<0x121>(x); return x; }
; __device__ __forceinline__ void scan_phase(const Args& a, LAS unsigned char* lds, int tid, int lane, int wave, int G, int bid) {
;     ...
;                         f32x2 yy = Sa * (f32x2){r4[0], r4[1]}; yy = __builtin_elementwise_fma(Sb, (f32x2){r4[2], r4[3]}, yy);
;                         float y = yy.x + yy.y;
;                         y = allred16_dpp(y);
;                         yk = fmaf(wsel[i], y, yk);
;                     }
;                     YB[(oh * 16 + c) * 16 + row] = yk;
;                 }
;             }
;             __syncthreads();
;             if (stager) { const int st = sid >> 3, r2 = (sid & 7) * 2; const f32x2 yv = *(const LAS f32x2*)(YB + st * 16 + r2); *(f32x2*)(YR + (tb + (size_t)ch * SC_CH + st) * 256 + h * 64 + v0 + r2) = yv; }
.Lsp_next:
	s_add_i32 s54, s54, 1
	s_cmpk_eq_i32 s54, 0x80
	s_cbranch_scc0 .Lsp_loop
	s_and_b64 vcc, exec, s[38:39]
	s_cbranch_vccz .Lsp_ep_s
	v_pk_mul_f32 v[90:91], v[84:85], v[184:185]
	v_pk_fma_f32 v[90:91], v[86:87], v[186:187], v[90:91]
	v_add_f32_e32 v118, v90, v91
	s_nop 1
	v_add_f32_dpp v118, v118, v118 row_ror:8 row_mask:0xf bank_mask:0xf bound_ctrl:1
	s_nop 1
	v_add_f32_dpp v118, v118, v118 row_ror:4 row_mask:0xf bank_mask:0xf bound_ctrl:1
	s_nop 1
	v_add_f32_dpp v118, v118, v118 row_ror:2 row_mask:0xf bank_mask:0xf bound_ctrl:1
	s_nop 1
	v_add_f32_dpp v118, v118, v118 row_ror:1 row_mask:0xf bank_mask:0xf bound_ctrl:1
	v_fmac_f32_e32 v244, v144, v118
	ds_write_b32 v126, v244 offset:1024
.Lsp_ep_s:
	s_waitcnt lgkmcnt(0)
	s_barrier
	s_and_b64 vcc, exec, s[38:39]
	s_cbranch_vccnz .LBB0_107
	s_movk_i32 s50, 0x7f
	s_mov_b32 s51, 1
	v_lshl_add_u32 v38, s51, 11, v125
	ds_read_b64 v[38:39], v38
	v_lshl_or_b32 v36, s50, 5, v2
	v_or_b32_e32 v36, s48, v36
	v_mov_b32_e32 v37, s49
	v_lshlrev_b64 v[36:37], 10, v[36:37]
	v_lshl_add_u64 v[36:37], v[116:117], 0, v[36:37]
	s_waitcnt lgkmcnt(0)
	global_store_dwordx2 v[36:37], v[38:39], off
	s_branch .LBB0_107
